# v15 + all four GEMM K loops: first trip peeled with C=0 on the first MFMA of every accumulator, the 128 per-unit accumulator clears removed
# speedup vs baseline: 1.0084x; 1.0041x over previous
; #define G_STAGE_B(bufoff, gbase) do { G_GLDS((const char*)(gbase) + voffB0, (bufoff) + ldsw); G_GLDS((const char*)(gbase) + vstep64 + voffB0, (bufoff) + ldsw + 8192); } while (0)
; #define G_STAGE_AU(bufoff, gbase) do { G_GLDS((const char*)(gbase) + voffA0, (bufoff) + ldsw); G_GLDS((const char*)(gbase) + vstep64 + voffA0, (bufoff) + ldsw + 8192); } while (0)
; #define X_LDA(b, h) do { if constexpr (MODE == 2) G_LDA8(A8, b, h); else G_LDA(At, b, h); } while (0)
; #define X_LDB0(b, h) do { if constexpr (MODE == 2) G_LDB8(B08, b, h); else G_LDB(B0, b, h); } while (0)
; #define X_LDB1(b, h) do { if constexpr (MODE == 2) G_LDB8(B18, b, h); else G_LDB(B1, b, h); } while (0)
; #define X_MMA0(ai, bj) do { if constexpr (MODE == 2) G_MMA8(ai, bj, A8, B08); else G_MMA(ai, bj, At, B0); } while (0)
; #define X_MMA1(ai, bj) do { if constexpr (MODE == 2) G_MMA8(ai, bj, A8, B18); else G_MMA(ai, bj, At, B1); } while (0)
; #define G_WAIT_V(n) asm volatile("s_waitcnt vmcnt(" #n ")" ::: "memory")
; #define G_WAIT_L(n) asm volatile("s_waitcnt lgkmcnt(" #n ")" ::: "memory")
; #define G_BAR __builtin_amdgcn_s_barrier()
; #define G_SCHED __builtin_amdgcn_sched_barrier(0)
;     ...
;         for (int t = 0; t < nt; t += 2) {
;             const bool last = (t == nt - 2);
;             const char* a1 = cA + (size_t)(t + 1) * kstep;
;             const char* a2 = last ? nA : cA + (size_t)(t + 2) * kstep; const char* b2 = last ? nB : cB + (size_t)(t + 2) * kstep;
;             const char* a3 = a2 + kstep; const char* b3 = b2 + kstep;
;             X_LDB0(0, 0); X_LDB1(0, 1); G_SCHED; X_LDA(0, 0); G_STAGE_AU(G_SA(1, 1), a1 + hstep);
;             G_WAIT_V(8); G_WAIT_L(0); G_BAR; X_MMA0(0, 0); X_MMA1(0, 1); G_BAR; G_SCHED;
;             X_LDA(0, 1); G_STAGE_B(G_SB(0, 0), b2); G_STAGE_B(G_SB(0, 1), b2 + hstep); G_STAGE_AU(G_SA(0, 0), a2);
;             G_WAIT_V(8); G_WAIT_L(0); G_BAR; X_MMA0(1, 0); X_MMA1(1, 1); G_BAR; G_SCHED;
;     ...
; #pragma unroll
;         for (int a = 0; a < 2; ++a)
; #pragma unroll
;             for (int b = 0; b < 2; ++b)
; #pragma unroll
;                 for (int m = 0; m < 4; ++m)
; #pragma unroll
;                     for (int n = 0; n < 2; ++n) acc[a][b][m][n] = (f32x4){0.f, 0.f, 0.f, 0.f};
.LBB0_202:
	s_lshl_b32 s16, s73, 8
	s_lshl_b64 s[6:7], s[16:17], 10
	s_add_u32 s54, s78, s6
	s_addc_u32 s55, s79, s7
	s_and_b64 s[6:7], s[36:37], exec
	s_cselect_b32 s3, s55, s1
	s_cselect_b32 s6, s54, s0
	s_ashr_i32 s53, s52, 31
	s_lshl_b64 s[10:11], s[52:53], 18
	s_add_u32 s56, s12, s10
	s_addc_u32 s57, s13, s11
	s_and_b64 s[10:11], s[36:37], exec
	s_cselect_b32 s7, s57, s9
	s_cselect_b32 s10, s56, s8
	s_add_u32 s0, s0, 0x20080
	s_addc_u32 s1, s1, 0
	s_add_u32 s8, s8, 0x100
	v_mov_b32_e32 v2, 0
	s_addc_u32 s9, s9, 0
	s_mov_b32 s11, -2
	s_waitcnt lgkmcnt(0)
.Lmy_peel_inproj_203:
	ds_read_b128 v[132:135], v217
	ds_read_b128 v[136:139], v217 offset:1024
	ds_read_b128 v[146:149], v217 offset:2048
	ds_read_b128 v[150:153], v217 offset:3072
	s_waitcnt vmcnt(0)
	ds_read_b128 v[154:157], v218
	ds_read_b128 v[158:161], v218 offset:1024
	ds_read_b128 v[162:165], v218 offset:2048
	ds_read_b128 v[166:169], v218 offset:3072
	s_add_u32 s16, s0, 0xfffe0080
	s_addc_u32 s38, s1, -1
	s_cmp_eq_u32 s11, 4
	s_cselect_b32 s39, s3, s38
	s_cselect_b32 s38, s6, s16
	s_cselect_b32 s95, s7, s9
	s_cselect_b32 s94, s10, s8
	s_mov_b32 m0, s69
	v_lshl_add_u64 v[202:203], s[0:1], 0, v[144:145]
	ds_read_b128 v[170:173], v219
	ds_read_b128 v[174:177], v219 offset:1024
	ds_read_b128 v[178:181], v219 offset:2048
	ds_read_b128 v[182:185], v219 offset:3072
	ds_read_b128 v[186:189], v219 offset:4096
	ds_read_b128 v[190:193], v219 offset:5120
	ds_read_b128 v[194:197], v219 offset:6144
	ds_read_b128 v[198:201], v219 offset:7168
	global_load_lds_dwordx4 v[202:203], off
	v_lshl_add_u64 v[202:203], v[202:203], 0, s[20:21]
	s_mov_b32 m0, s72
	s_nop 0
	global_load_lds_dwordx4 v[202:203], off
	s_waitcnt vmcnt(8)
	s_waitcnt lgkmcnt(0)
	s_barrier
	s_setprio 1
	s_waitcnt lgkmcnt(0)
	v_mfma_i32_16x16x64_i8 v[128:131], v[132:135], v[170:173], 0
	v_mfma_i32_16x16x64_i8 v[124:127], v[146:149], v[170:173], 0
	v_mfma_i32_16x16x64_i8 v[120:123], v[132:135], v[178:181], 0
	v_mfma_i32_16x16x64_i8 v[116:119], v[146:149], v[178:181], 0
	v_mfma_i32_16x16x64_i8 v[112:115], v[132:135], v[186:189], 0
	v_mfma_i32_16x16x64_i8 v[108:111], v[146:149], v[186:189], 0
	v_mfma_i32_16x16x64_i8 v[104:107], v[132:135], v[194:197], 0
	v_mfma_i32_16x16x64_i8 v[100:103], v[146:149], v[194:197], 0
	v_mfma_i32_16x16x64_i8 v[128:131], v[136:139], v[174:177], v[128:131]
	v_mfma_i32_16x16x64_i8 v[124:127], v[150:153], v[174:177], v[124:127]
	v_mfma_i32_16x16x64_i8 v[120:123], v[136:139], v[182:185], v[120:123]
	v_mfma_i32_16x16x64_i8 v[116:119], v[150:153], v[182:185], v[116:119]
	v_mfma_i32_16x16x64_i8 v[112:115], v[136:139], v[190:193], v[112:115]
	v_mfma_i32_16x16x64_i8 v[108:111], v[150:153], v[190:193], v[108:111]
	v_mfma_i32_16x16x64_i8 v[104:107], v[136:139], v[198:201], v[104:107]
	v_mfma_i32_16x16x64_i8 v[100:103], v[150:153], v[198:201], v[100:103]
	s_setprio 0
	s_setprio 1
	v_mfma_i32_16x16x64_i8 v[62:65], v[154:157], v[170:173], 0
	v_mfma_i32_16x16x64_i8 v[58:61], v[162:165], v[170:173], 0
	v_mfma_i32_16x16x64_i8 v[54:57], v[154:157], v[178:181], 0
	v_mfma_i32_16x16x64_i8 v[50:53], v[162:165], v[178:181], 0
	v_mfma_i32_16x16x64_i8 v[46:49], v[154:157], v[186:189], 0
	v_mfma_i32_16x16x64_i8 v[42:45], v[162:165], v[186:189], 0
	v_mfma_i32_16x16x64_i8 v[38:41], v[154:157], v[194:197], 0
	v_mfma_i32_16x16x64_i8 v[34:37], v[162:165], v[194:197], 0
	v_mfma_i32_16x16x64_i8 v[62:65], v[158:161], v[174:177], v[62:65]
	v_mfma_i32_16x16x64_i8 v[58:61], v[166:169], v[174:177], v[58:61]
	v_mfma_i32_16x16x64_i8 v[54:57], v[158:161], v[182:185], v[54:57]
	v_mfma_i32_16x16x64_i8 v[50:53], v[166:169], v[182:185], v[50:53]
	v_mfma_i32_16x16x64_i8 v[46:49], v[158:161], v[190:193], v[46:49]
	v_mfma_i32_16x16x64_i8 v[42:45], v[166:169], v[190:193], v[42:45]
	v_mfma_i32_16x16x64_i8 v[38:41], v[158:161], v[198:201], v[38:41]
	v_mfma_i32_16x16x64_i8 v[34:37], v[166:169], v[198:201], v[34:37]
	s_setprio 0
	s_barrier
	s_mov_b32 m0, s26
	v_lshl_add_u64 v[202:203], s[94:95], 0, v[142:143]
	ds_read_b128 v[170:173], v219 offset:16384
	ds_read_b128 v[174:177], v219 offset:17408
	ds_read_b128 v[178:181], v219 offset:18432
	ds_read_b128 v[182:185], v219 offset:19456
	ds_read_b128 v[186:189], v219 offset:20480
	ds_read_b128 v[190:193], v219 offset:21504
	ds_read_b128 v[194:197], v219 offset:22528
	ds_read_b128 v[198:201], v219 offset:23552
	global_load_lds_dwordx4 v[202:203], off
	v_lshl_add_u64 v[204:205], v[202:203], 0, s[20:21]
	s_mov_b32 m0, s27
	s_nop 0
	global_load_lds_dwordx4 v[204:205], off
	v_lshl_add_u64 v[204:205], v[202:203], 0, s[18:19]
	s_mov_b32 m0, s28
	s_nop 0
	global_load_lds_dwordx4 v[204:205], off
	v_lshl_add_u64 v[204:205], v[202:203], 0, s[92:93]
	s_mov_b32 m0, s29
	s_nop 0
	global_load_lds_dwordx4 v[204:205], off
	v_lshl_add_u64 v[204:205], s[38:39], 0, v[140:141]
	s_mov_b32 m0, s25
	v_lshl_add_u64 v[206:207], v[204:205], 0, s[20:21]
	global_load_lds_dwordx4 v[204:205], off
	s_mov_b32 m0, s58
	s_nop 0
	global_load_lds_dwordx4 v[206:207], off
	s_waitcnt vmcnt(8)
	s_waitcnt lgkmcnt(0)
	s_barrier
; #define G_STAGE_AU(bufoff, gbase) do { G_GLDS((const char*)(gbase) + voffA0, (bufoff) + ldsw); G_GLDS((const char*)(gbase) + vstep64 + voffA0, (bufoff) + ldsw + 8192); } while (0)
; #define X_LDA(b, h) do { if constexpr (MODE == 2) G_LDA8(A8, b, h); else G_LDA(At, b, h); } while (0)
; #define X_LDB0(b, h) do { if constexpr (MODE == 2) G_LDB8(B08, b, h); else G_LDB(B0, b, h); } while (0)
; #define X_LDB1(b, h) do { if constexpr (MODE == 2) G_LDB8(B18, b, h); else G_LDB(B1, b, h); } while (0)
; #define X_MMA0(ai, bj) do { if constexpr (MODE == 2) G_MMA8(ai, bj, A8, B08); else G_MMA(ai, bj, At, B0); } while (0)
; #define X_MMA1(ai, bj) do { if constexpr (MODE == 2) G_MMA8(ai, bj, A8, B18); else G_MMA(ai, bj, At, B1); } while (0)
; #define G_WAIT_V(n) asm volatile("s_waitcnt vmcnt(" #n ")" ::: "memory")
; #define G_WAIT_L(n) asm volatile("s_waitcnt lgkmcnt(" #n ")" ::: "memory")
; #define G_BAR __builtin_amdgcn_s_barrier()
; #define G_SCHED __builtin_amdgcn_sched_barrier(0)
;     ...
;             G_WAIT_V(8); G_WAIT_L(0); G_BAR; X_MMA0(1, 0); X_MMA1(1, 1); G_BAR; G_SCHED;
;             X_LDB0(1, 0); X_LDB1(1, 1); G_SCHED; X_LDA(1, 0); G_STAGE_AU(G_SA(0, 1), a2 + hstep);
;             G_WAIT_V(8); G_WAIT_L(0); G_BAR; X_MMA0(0, 0); X_MMA1(0, 1); G_BAR; G_SCHED;
	s_setprio 1
	s_waitcnt lgkmcnt(0)
	v_mfma_i32_16x16x64_i8 v[96:99], v[132:135], v[170:173], 0
	v_mfma_i32_16x16x64_i8 v[92:95], v[146:149], v[170:173], 0
	v_mfma_i32_16x16x64_i8 v[88:91], v[132:135], v[178:181], 0
	v_mfma_i32_16x16x64_i8 v[84:87], v[146:149], v[178:181], 0
	v_mfma_i32_16x16x64_i8 v[80:83], v[132:135], v[186:189], 0
	v_mfma_i32_16x16x64_i8 v[76:79], v[146:149], v[186:189], 0
	v_mfma_i32_16x16x64_i8 v[72:75], v[132:135], v[194:197], 0
	v_mfma_i32_16x16x64_i8 v[68:71], v[146:149], v[194:197], 0
	v_mfma_i32_16x16x64_i8 v[96:99], v[136:139], v[174:177], v[96:99]
	v_mfma_i32_16x16x64_i8 v[92:95], v[150:153], v[174:177], v[92:95]
	v_mfma_i32_16x16x64_i8 v[88:91], v[136:139], v[182:185], v[88:91]
	v_mfma_i32_16x16x64_i8 v[84:87], v[150:153], v[182:185], v[84:87]
	v_mfma_i32_16x16x64_i8 v[80:83], v[136:139], v[190:193], v[80:83]
	v_mfma_i32_16x16x64_i8 v[76:79], v[150:153], v[190:193], v[76:79]
	v_mfma_i32_16x16x64_i8 v[72:75], v[136:139], v[198:201], v[72:75]
	v_mfma_i32_16x16x64_i8 v[68:71], v[150:153], v[198:201], v[68:71]
	s_setprio 0
	s_setprio 1
	v_mfma_i32_16x16x64_i8 v[30:33], v[154:157], v[170:173], 0
	v_mfma_i32_16x16x64_i8 v[26:29], v[162:165], v[170:173], 0
	v_mfma_i32_16x16x64_i8 v[22:25], v[154:157], v[178:181], 0
	v_mfma_i32_16x16x64_i8 v[18:21], v[162:165], v[178:181], 0
	v_mfma_i32_16x16x64_i8 v[14:17], v[154:157], v[186:189], 0
	v_mfma_i32_16x16x64_i8 v[10:13], v[162:165], v[186:189], 0
	v_mfma_i32_16x16x64_i8 v[6:9], v[154:157], v[194:197], 0
	v_mfma_i32_16x16x64_i8 v[2:5], v[162:165], v[194:197], 0
	v_mfma_i32_16x16x64_i8 v[30:33], v[158:161], v[174:177], v[30:33]
	v_mfma_i32_16x16x64_i8 v[26:29], v[166:169], v[174:177], v[26:29]
	v_mfma_i32_16x16x64_i8 v[22:25], v[158:161], v[182:185], v[22:25]
	v_mfma_i32_16x16x64_i8 v[18:21], v[166:169], v[182:185], v[18:21]
	v_mfma_i32_16x16x64_i8 v[14:17], v[158:161], v[190:193], v[14:17]
	v_mfma_i32_16x16x64_i8 v[10:13], v[166:169], v[190:193], v[10:13]
	v_mfma_i32_16x16x64_i8 v[6:9], v[158:161], v[198:201], v[6:9]
	v_mfma_i32_16x16x64_i8 v[2:5], v[166:169], v[198:201], v[2:5]
	s_setprio 0
	s_barrier
	ds_read_b128 v[132:135], v231
	ds_read_b128 v[136:139], v231 offset:1024
	ds_read_b128 v[146:149], v231 offset:2048
	ds_read_b128 v[150:153], v231 offset:3072
	ds_read_b128 v[154:157], v232
	ds_read_b128 v[158:161], v232 offset:1024
	ds_read_b128 v[162:165], v232 offset:2048
	ds_read_b128 v[166:169], v232 offset:3072
	s_mov_b32 m0, s59
	v_lshl_add_u64 v[206:207], v[204:205], 0, s[18:19]
	ds_read_b128 v[170:173], v219 offset:32768
	ds_read_b128 v[174:177], v219 offset:33792
	ds_read_b128 v[178:181], v219 offset:34816
	ds_read_b128 v[182:185], v219 offset:35840
	ds_read_b128 v[186:189], v219 offset:36864
	ds_read_b128 v[190:193], v219 offset:37888
	ds_read_b128 v[194:197], v219 offset:38912
	ds_read_b128 v[198:201], v219 offset:39936
	global_load_lds_dwordx4 v[206:207], off
	v_lshl_add_u64 v[206:207], v[204:205], 0, s[92:93]
	s_mov_b32 m0, s60
	s_nop 0
	global_load_lds_dwordx4 v[206:207], off
	s_waitcnt vmcnt(8)
	s_waitcnt lgkmcnt(0)
	s_barrier
	s_setprio 1
	s_waitcnt lgkmcnt(0)
	v_mfma_i32_16x16x64_i8 v[128:131], v[132:135], v[170:173], v[128:131]
	v_mfma_i32_16x16x64_i8 v[124:127], v[146:149], v[170:173], v[124:127]
	v_mfma_i32_16x16x64_i8 v[120:123], v[132:135], v[178:181], v[120:123]
	v_mfma_i32_16x16x64_i8 v[116:119], v[146:149], v[178:181], v[116:119]
	v_mfma_i32_16x16x64_i8 v[112:115], v[132:135], v[186:189], v[112:115]
	v_mfma_i32_16x16x64_i8 v[108:111], v[146:149], v[186:189], v[108:111]
	v_mfma_i32_16x16x64_i8 v[104:107], v[132:135], v[194:197], v[104:107]
	v_mfma_i32_16x16x64_i8 v[100:103], v[146:149], v[194:197], v[100:103]
	v_mfma_i32_16x16x64_i8 v[128:131], v[136:139], v[174:177], v[128:131]
	v_mfma_i32_16x16x64_i8 v[124:127], v[150:153], v[174:177], v[124:127]
	v_mfma_i32_16x16x64_i8 v[120:123], v[136:139], v[182:185], v[120:123]
	v_mfma_i32_16x16x64_i8 v[116:119], v[150:153], v[182:185], v[116:119]
	v_mfma_i32_16x16x64_i8 v[112:115], v[136:139], v[190:193], v[112:115]
	v_mfma_i32_16x16x64_i8 v[108:111], v[150:153], v[190:193], v[108:111]
	v_mfma_i32_16x16x64_i8 v[104:107], v[136:139], v[198:201], v[104:107]
	v_mfma_i32_16x16x64_i8 v[100:103], v[150:153], v[198:201], v[100:103]
	s_setprio 0
	s_setprio 1
	v_mfma_i32_16x16x64_i8 v[62:65], v[154:157], v[170:173], v[62:65]
	v_mfma_i32_16x16x64_i8 v[58:61], v[162:165], v[170:173], v[58:61]
	v_mfma_i32_16x16x64_i8 v[54:57], v[154:157], v[178:181], v[54:57]
	v_mfma_i32_16x16x64_i8 v[50:53], v[162:165], v[178:181], v[50:53]
	v_mfma_i32_16x16x64_i8 v[46:49], v[154:157], v[186:189], v[46:49]
	v_mfma_i32_16x16x64_i8 v[42:45], v[162:165], v[186:189], v[42:45]
	v_mfma_i32_16x16x64_i8 v[38:41], v[154:157], v[194:197], v[38:41]
	v_mfma_i32_16x16x64_i8 v[34:37], v[162:165], v[194:197], v[34:37]
	v_mfma_i32_16x16x64_i8 v[62:65], v[158:161], v[174:177], v[62:65]
	v_mfma_i32_16x16x64_i8 v[58:61], v[166:169], v[174:177], v[58:61]
	v_mfma_i32_16x16x64_i8 v[54:57], v[158:161], v[182:185], v[54:57]
	v_mfma_i32_16x16x64_i8 v[50:53], v[166:169], v[182:185], v[50:53]
	v_mfma_i32_16x16x64_i8 v[46:49], v[158:161], v[190:193], v[46:49]
	v_mfma_i32_16x16x64_i8 v[42:45], v[166:169], v[190:193], v[42:45]
	v_mfma_i32_16x16x64_i8 v[38:41], v[158:161], v[198:201], v[38:41]
	v_mfma_i32_16x16x64_i8 v[34:37], v[166:169], v[198:201], v[34:37]
	s_setprio 0
	s_barrier
; #define G_STAGE_B(bufoff, gbase) do { G_GLDS((const char*)(gbase) + voffB0, (bufoff) + ldsw); G_GLDS((const char*)(gbase) + vstep64 + voffB0, (bufoff) + ldsw + 8192); } while (0)
; #define G_STAGE_AU(bufoff, gbase) do { G_GLDS((const char*)(gbase) + voffA0, (bufoff) + ldsw); G_GLDS((const char*)(gbase) + vstep64 + voffA0, (bufoff) + ldsw + 8192); } while (0)
; #define X_LDA(b, h) do { if constexpr (MODE == 2) G_LDA8(A8, b, h); else G_LDA(At, b, h); } while (0)
; #define X_MMA0(ai, bj) do { if constexpr (MODE == 2) G_MMA8(ai, bj, A8, B08); else G_MMA(ai, bj, At, B0); } while (0)
; #define X_MMA1(ai, bj) do { if constexpr (MODE == 2) G_MMA8(ai, bj, A8, B18); else G_MMA(ai, bj, At, B1); } while (0)
; #define G_WAIT_V(n) asm volatile("s_waitcnt vmcnt(" #n ")" ::: "memory")
; #define G_WAIT_L(n) asm volatile("s_waitcnt lgkmcnt(" #n ")" ::: "memory")
; #define G_BAR __builtin_amdgcn_s_barrier()
; #define G_SCHED __builtin_amdgcn_sched_barrier(0)
;     ...
;             X_LDA(1, 1); G_STAGE_B(G_SB(1, 0), b3); G_STAGE_B(G_SB(1, 1), b3 + hstep); G_STAGE_AU(G_SA(1, 0), a3);
;             G_WAIT_V(8); G_WAIT_L(0); G_BAR; X_MMA0(1, 0); X_MMA1(1, 1); G_BAR; G_SCHED;
;         }
	s_mov_b32 m0, s61
	v_lshl_add_u64 v[206:207], v[202:203], 0, s[82:83]
	ds_read_b128 v[170:173], v219 offset:49152
	ds_read_b128 v[174:177], v219 offset:50176
	ds_read_b128 v[178:181], v219 offset:51200
	ds_read_b128 v[182:185], v219 offset:52224
	ds_read_b128 v[186:189], v219 offset:53248
	ds_read_b128 v[190:193], v219 offset:54272
	ds_read_b128 v[194:197], v219 offset:55296
	ds_read_b128 v[198:201], v219 offset:56320
	global_load_lds_dwordx4 v[206:207], off
	v_lshl_add_u64 v[206:207], v[202:203], 0, s[22:23]
	s_mov_b32 m0, s62
	s_nop 0
	global_load_lds_dwordx4 v[206:207], off
	v_lshl_add_u64 v[206:207], v[202:203], 0, s[88:89]
	s_mov_b32 m0, s65
	v_lshl_add_u64 v[202:203], v[202:203], 0, s[74:75]
	global_load_lds_dwordx4 v[206:207], off
	s_mov_b32 m0, s66
	s_nop 0
	global_load_lds_dwordx4 v[202:203], off
	v_lshl_add_u64 v[202:203], v[204:205], 0, s[82:83]
	s_mov_b32 m0, s63
	s_nop 0
	global_load_lds_dwordx4 v[202:203], off
	v_lshl_add_u64 v[202:203], v[204:205], 0, s[22:23]
	s_mov_b32 m0, s64
	s_nop 0
	global_load_lds_dwordx4 v[202:203], off
	s_waitcnt vmcnt(8)
	s_waitcnt lgkmcnt(0)
	s_barrier
	s_setprio 1
	s_waitcnt lgkmcnt(0)
	v_mfma_i32_16x16x64_i8 v[96:99], v[132:135], v[170:173], v[96:99]
	v_mfma_i32_16x16x64_i8 v[92:95], v[146:149], v[170:173], v[92:95]
	v_mfma_i32_16x16x64_i8 v[88:91], v[132:135], v[178:181], v[88:91]
	v_mfma_i32_16x16x64_i8 v[84:87], v[146:149], v[178:181], v[84:87]
	v_mfma_i32_16x16x64_i8 v[80:83], v[132:135], v[186:189], v[80:83]
	v_mfma_i32_16x16x64_i8 v[76:79], v[146:149], v[186:189], v[76:79]
	v_mfma_i32_16x16x64_i8 v[72:75], v[132:135], v[194:197], v[72:75]
	v_mfma_i32_16x16x64_i8 v[68:71], v[146:149], v[194:197], v[68:71]
	v_mfma_i32_16x16x64_i8 v[96:99], v[136:139], v[174:177], v[96:99]
	v_mfma_i32_16x16x64_i8 v[92:95], v[150:153], v[174:177], v[92:95]
	v_mfma_i32_16x16x64_i8 v[88:91], v[136:139], v[182:185], v[88:91]
	v_mfma_i32_16x16x64_i8 v[84:87], v[150:153], v[182:185], v[84:87]
	v_mfma_i32_16x16x64_i8 v[80:83], v[136:139], v[190:193], v[80:83]
	v_mfma_i32_16x16x64_i8 v[76:79], v[150:153], v[190:193], v[76:79]
	v_mfma_i32_16x16x64_i8 v[72:75], v[136:139], v[198:201], v[72:75]
	v_mfma_i32_16x16x64_i8 v[68:71], v[150:153], v[198:201], v[68:71]
	s_setprio 0
	s_setprio 1
	v_mfma_i32_16x16x64_i8 v[30:33], v[154:157], v[170:173], v[30:33]
	v_mfma_i32_16x16x64_i8 v[26:29], v[162:165], v[170:173], v[26:29]
	v_mfma_i32_16x16x64_i8 v[22:25], v[154:157], v[178:181], v[22:25]
	v_mfma_i32_16x16x64_i8 v[18:21], v[162:165], v[178:181], v[18:21]
	v_mfma_i32_16x16x64_i8 v[14:17], v[154:157], v[186:189], v[14:17]
	v_mfma_i32_16x16x64_i8 v[10:13], v[162:165], v[186:189], v[10:13]
	v_mfma_i32_16x16x64_i8 v[6:9], v[154:157], v[194:197], v[6:9]
	v_mfma_i32_16x16x64_i8 v[2:5], v[162:165], v[194:197], v[2:5]
	v_mfma_i32_16x16x64_i8 v[30:33], v[158:161], v[174:177], v[30:33]
	v_mfma_i32_16x16x64_i8 v[26:29], v[166:169], v[174:177], v[26:29]
	v_mfma_i32_16x16x64_i8 v[22:25], v[158:161], v[182:185], v[22:25]
	v_mfma_i32_16x16x64_i8 v[18:21], v[166:169], v[182:185], v[18:21]
	v_mfma_i32_16x16x64_i8 v[14:17], v[158:161], v[190:193], v[14:17]
	v_mfma_i32_16x16x64_i8 v[10:13], v[166:169], v[190:193], v[10:13]
	v_mfma_i32_16x16x64_i8 v[6:9], v[158:161], v[198:201], v[6:9]
	v_mfma_i32_16x16x64_i8 v[2:5], v[166:169], v[198:201], v[2:5]
	s_setprio 0
	s_barrier
	s_add_i32 s11, s11, 2
	s_add_u32 s0, s0, 0x100
	s_addc_u32 s1, s1, 0
	s_add_u32 s8, s8, 0x100
	s_addc_u32 s9, s9, 0
	s_cmp_gt_u32 s11, 5
	s_cbranch_scc1 .Lmy_peel_inproj_exit

; #define G_BAR __builtin_amdgcn_s_barrier()
;     ...
;         if (wr == 0) G_BAR;
.Lmy_peel_inproj_exit:
	s_and_b64 vcc, exec, s[50:51]
	s_cbranch_vccz .LBB0_206
	s_barrier

; #define G_STAGE_B(bufoff, gbase) do { G_GLDS((const char*)(gbase) + voffB0, (bufoff) + ldsw); G_GLDS((const char*)(gbase) + vstep64 + voffB0, (bufoff) + ldsw + 8192); } while (0)
; #define G_STAGE_AU(bufoff, gbase) do { G_GLDS((const char*)(gbase) + voffA0, (bufoff) + ldsw); G_GLDS((const char*)(gbase) + vstep64 + voffA0, (bufoff) + ldsw + 8192); } while (0)
; #define X_LDA(b, h) do { if constexpr (MODE == 2) G_LDA8(A8, b, h); else G_LDA(At, b, h); } while (0)
; #define X_LDB0(b, h) do { if constexpr (MODE == 2) G_LDB8(B08, b, h); else G_LDB(B0, b, h); } while (0)
; #define X_LDB1(b, h) do { if constexpr (MODE == 2) G_LDB8(B18, b, h); else G_LDB(B1, b, h); } while (0)
; #define X_MMA0(ai, bj) do { if constexpr (MODE == 2) G_MMA8(ai, bj, A8, B08); else G_MMA(ai, bj, At, B0); } while (0)
; #define X_MMA1(ai, bj) do { if constexpr (MODE == 2) G_MMA8(ai, bj, A8, B18); else G_MMA(ai, bj, At, B1); } while (0)
; #define G_WAIT_V(n) asm volatile("s_waitcnt vmcnt(" #n ")" ::: "memory")
; #define G_WAIT_L(n) asm volatile("s_waitcnt lgkmcnt(" #n ")" ::: "memory")
; #define G_BAR __builtin_amdgcn_s_barrier()
; #define G_SCHED __builtin_amdgcn_sched_barrier(0)
;     ...
;         for (int t = 0; t < nt; t += 2) {
;             const bool last = (t == nt - 2);
;             const char* a1 = cA + (size_t)(t + 1) * kstep;
;             const char* a2 = last ? nA : cA + (size_t)(t + 2) * kstep; const char* b2 = last ? nB : cB + (size_t)(t + 2) * kstep;
;             const char* a3 = a2 + kstep; const char* b3 = b2 + kstep;
;             X_LDB0(0, 0); X_LDB1(0, 1); G_SCHED; X_LDA(0, 0); G_STAGE_AU(G_SA(1, 1), a1 + hstep);
;             G_WAIT_V(8); G_WAIT_L(0); G_BAR; X_MMA0(0, 0); X_MMA1(0, 1); G_BAR; G_SCHED;
;             X_LDA(0, 1); G_STAGE_B(G_SB(0, 0), b2); G_STAGE_B(G_SB(0, 1), b2 + hstep); G_STAGE_AU(G_SA(0, 0), a2);
;             G_WAIT_V(8); G_WAIT_L(0); G_BAR; X_MMA0(1, 0); X_MMA1(1, 1); G_BAR; G_SCHED;
;     ...
; #pragma unroll
;         for (int a = 0; a < 2; ++a)
; #pragma unroll
;             for (int b = 0; b < 2; ++b)
; #pragma unroll
;                 for (int m = 0; m < 4; ++m)
; #pragma unroll
;                     for (int n = 0; n < 2; ++n) acc[a][b][m][n] = (f32x4){0.f, 0.f, 0.f, 0.f};
.LBB0_706:
	s_lshl_b32 s16, s55, 8
	s_lshl_b64 s[12:13], s[16:17], 11
	s_add_u32 s12, s78, s12
	s_addc_u32 s13, s79, s13
	s_and_b64 s[38:39], s[36:37], exec
	s_cselect_b32 s16, s13, s41
	s_cselect_b32 s56, s12, s40
	s_ashr_i32 s11, s10, 31
	s_lshl_b64 s[38:39], s[10:11], 19
	s_add_u32 s38, s3, s38
	s_addc_u32 s39, s6, s39
	s_and_b64 s[58:59], s[36:37], exec
	s_cselect_b32 s11, s39, s43
	s_cselect_b32 s57, s38, s42
	s_add_u32 s40, s40, 0x40080
	s_addc_u32 s41, s41, 0
	s_add_u32 s42, s42, 0x100
	v_mov_b32_e32 v2, 0
	s_mov_b64 s[30:31], 0x60000
	s_addc_u32 s43, s43, 0
	s_mov_b32 s58, -2
	s_waitcnt lgkmcnt(0)
	s_mov_b64 s[66:67], 0x40080
	s_mov_b64 s[68:69], 0x60080
.Lmy_peel_outproj_707:
	v_add_u32_e32 v152, 0x10000, v138
	v_add_u32_e32 v168, 0x14000, v138
	ds_read_b128 v[140:143], v152
	ds_read_b128 v[144:147], v152 offset:1024
	ds_read_b128 v[148:151], v152 offset:2048
	ds_read_b128 v[152:155], v152 offset:3072
	ds_read_b128 v[156:159], v168
	ds_read_b128 v[160:163], v168 offset:1024
	ds_read_b128 v[164:167], v168 offset:2048
	ds_read_b128 v[168:171], v168 offset:3072
	s_add_u32 s59, s40, 0xfffc0080
	s_addc_u32 s60, s41, -1
	s_cmp_eq_u32 s58, 12
	s_cselect_b32 s61, s16, s60
	s_cselect_b32 s60, s56, s59
	s_cselect_b32 s63, s11, s43
	s_cselect_b32 s62, s57, s42
	v_lshl_add_u64 v[204:205], s[40:41], 0, v[134:135]
	s_add_i32 m0, s7, 0xc000
	ds_read_b128 v[172:175], v139
	ds_read_b128 v[176:179], v139 offset:1024
	ds_read_b128 v[180:183], v139 offset:2048
	ds_read_b128 v[184:187], v139 offset:3072
	ds_read_b128 v[188:191], v139 offset:4096
	ds_read_b128 v[192:195], v139 offset:5120
	ds_read_b128 v[196:199], v139 offset:6144
	ds_read_b128 v[200:203], v139 offset:7168
	global_load_lds_dwordx4 v[204:205], off
	v_lshl_add_u64 v[204:205], v[204:205], 0, s[18:19]
	s_add_i32 m0, s7, 0xe000
	s_nop 0
	global_load_lds_dwordx4 v[204:205], off
	s_waitcnt vmcnt(8)
	s_waitcnt lgkmcnt(0)
	s_barrier
	s_setprio 1
	s_waitcnt lgkmcnt(0)
	v_mfma_f32_16x16x32_bf16 v[128:131], v[140:143], v[172:175], 0
	v_mfma_f32_16x16x32_bf16 v[124:127], v[148:151], v[172:175], 0
	v_mfma_f32_16x16x32_bf16 v[120:123], v[140:143], v[180:183], 0
	v_mfma_f32_16x16x32_bf16 v[116:119], v[148:151], v[180:183], 0
	v_mfma_f32_16x16x32_bf16 v[104:107], v[140:143], v[188:191], 0
	v_mfma_f32_16x16x32_bf16 v[100:103], v[148:151], v[188:191], 0
	v_mfma_f32_16x16x32_bf16 v[88:91], v[140:143], v[196:199], 0
	v_mfma_f32_16x16x32_bf16 v[84:87], v[148:151], v[196:199], 0
	v_mfma_f32_16x16x32_bf16 v[128:131], v[144:147], v[176:179], v[128:131]
	v_mfma_f32_16x16x32_bf16 v[124:127], v[152:155], v[176:179], v[124:127]
	v_mfma_f32_16x16x32_bf16 v[120:123], v[144:147], v[184:187], v[120:123]
	v_mfma_f32_16x16x32_bf16 v[116:119], v[152:155], v[184:187], v[116:119]
	v_mfma_f32_16x16x32_bf16 v[104:107], v[144:147], v[192:195], v[104:107]
	v_mfma_f32_16x16x32_bf16 v[100:103], v[152:155], v[192:195], v[100:103]
	v_mfma_f32_16x16x32_bf16 v[88:91], v[144:147], v[200:203], v[88:91]
	v_mfma_f32_16x16x32_bf16 v[84:87], v[152:155], v[200:203], v[84:87]
	s_setprio 0
	s_setprio 1
	v_mfma_f32_16x16x32_bf16 v[112:115], v[156:159], v[172:175], 0
	v_mfma_f32_16x16x32_bf16 v[108:111], v[164:167], v[172:175], 0
	v_mfma_f32_16x16x32_bf16 v[96:99], v[156:159], v[180:183], 0
	v_mfma_f32_16x16x32_bf16 v[92:95], v[164:167], v[180:183], 0
	v_mfma_f32_16x16x32_bf16 v[80:83], v[156:159], v[188:191], 0
	v_mfma_f32_16x16x32_bf16 v[76:79], v[164:167], v[188:191], 0
	v_mfma_f32_16x16x32_bf16 v[72:75], v[156:159], v[196:199], 0
	v_mfma_f32_16x16x32_bf16 v[68:71], v[164:167], v[196:199], 0
	v_mfma_f32_16x16x32_bf16 v[112:115], v[160:163], v[176:179], v[112:115]
	v_mfma_f32_16x16x32_bf16 v[108:111], v[168:171], v[176:179], v[108:111]
	v_mfma_f32_16x16x32_bf16 v[96:99], v[160:163], v[184:187], v[96:99]
	v_mfma_f32_16x16x32_bf16 v[92:95], v[168:171], v[184:187], v[92:95]
	v_mfma_f32_16x16x32_bf16 v[80:83], v[160:163], v[192:195], v[80:83]
	v_mfma_f32_16x16x32_bf16 v[76:79], v[168:171], v[192:195], v[76:79]
	v_mfma_f32_16x16x32_bf16 v[72:75], v[160:163], v[200:203], v[72:75]
	v_mfma_f32_16x16x32_bf16 v[68:71], v[168:171], v[200:203], v[68:71]
	s_setprio 0
	s_barrier
	s_mov_b32 m0, s26
	v_lshl_add_u64 v[204:205], s[62:63], 0, v[66:67]
	ds_read_b128 v[172:175], v139 offset:16384
	ds_read_b128 v[176:179], v139 offset:17408
	ds_read_b128 v[180:183], v139 offset:18432
	ds_read_b128 v[184:187], v139 offset:19456
	ds_read_b128 v[188:191], v139 offset:20480
	ds_read_b128 v[192:195], v139 offset:21504
	ds_read_b128 v[196:199], v139 offset:22528
	ds_read_b128 v[200:203], v139 offset:23552
	global_load_lds_dwordx4 v[204:205], off
	v_lshl_add_u64 v[206:207], v[204:205], 0, s[18:19]
	s_mov_b32 m0, s27
	s_nop 0
	global_load_lds_dwordx4 v[206:207], off
	v_lshl_add_u64 v[206:207], v[204:205], 0, s[96:97]
	s_mov_b32 m0, s28
	s_nop 0
	global_load_lds_dwordx4 v[206:207], off
	v_lshl_add_u64 v[206:207], v[204:205], 0, s[30:31]
	s_mov_b32 m0, s29
	s_nop 0
	global_load_lds_dwordx4 v[206:207], off
	v_lshl_add_u64 v[206:207], s[60:61], 0, v[132:133]
	s_mov_b32 m0, s7
	v_lshl_add_u64 v[208:209], v[206:207], 0, s[18:19]
	global_load_lds_dwordx4 v[206:207], off
	s_mov_b32 m0, s44
	s_nop 0
	global_load_lds_dwordx4 v[208:209], off
	s_waitcnt vmcnt(8)
	s_waitcnt lgkmcnt(0)
	s_barrier
; #define G_STAGE_AU(bufoff, gbase) do { G_GLDS((const char*)(gbase) + voffA0, (bufoff) + ldsw); G_GLDS((const char*)(gbase) + vstep64 + voffA0, (bufoff) + ldsw + 8192); } while (0)
; #define X_LDA(b, h) do { if constexpr (MODE == 2) G_LDA8(A8, b, h); else G_LDA(At, b, h); } while (0)
; #define X_LDB0(b, h) do { if constexpr (MODE == 2) G_LDB8(B08, b, h); else G_LDB(B0, b, h); } while (0)
; #define X_LDB1(b, h) do { if constexpr (MODE == 2) G_LDB8(B18, b, h); else G_LDB(B1, b, h); } while (0)
; #define X_MMA0(ai, bj) do { if constexpr (MODE == 2) G_MMA8(ai, bj, A8, B08); else G_MMA(ai, bj, At, B0); } while (0)
; #define X_MMA1(ai, bj) do { if constexpr (MODE == 2) G_MMA8(ai, bj, A8, B18); else G_MMA(ai, bj, At, B1); } while (0)
; #define G_WAIT_V(n) asm volatile("s_waitcnt vmcnt(" #n ")" ::: "memory")
; #define G_WAIT_L(n) asm volatile("s_waitcnt lgkmcnt(" #n ")" ::: "memory")
; #define G_BAR __builtin_amdgcn_s_barrier()
; #define G_SCHED __builtin_amdgcn_sched_barrier(0)
;     ...
;             G_WAIT_V(8); G_WAIT_L(0); G_BAR; X_MMA0(1, 0); X_MMA1(1, 1); G_BAR; G_SCHED;
;             X_LDB0(1, 0); X_LDB1(1, 1); G_SCHED; X_LDA(1, 0); G_STAGE_AU(G_SA(0, 1), a2 + hstep);
;             G_WAIT_V(8); G_WAIT_L(0); G_BAR; X_MMA0(0, 0); X_MMA1(0, 1); G_BAR; G_SCHED;
	s_setprio 1
	s_waitcnt lgkmcnt(0)
	v_mfma_f32_16x16x32_bf16 v[62:65], v[140:143], v[172:175], 0
	v_mfma_f32_16x16x32_bf16 v[58:61], v[148:151], v[172:175], 0
	v_mfma_f32_16x16x32_bf16 v[54:57], v[140:143], v[180:183], 0
	v_mfma_f32_16x16x32_bf16 v[50:53], v[148:151], v[180:183], 0
	v_mfma_f32_16x16x32_bf16 v[38:41], v[140:143], v[188:191], 0
	v_mfma_f32_16x16x32_bf16 v[34:37], v[148:151], v[188:191], 0
	v_mfma_f32_16x16x32_bf16 v[22:25], v[140:143], v[196:199], 0
	v_mfma_f32_16x16x32_bf16 v[18:21], v[148:151], v[196:199], 0
	v_mfma_f32_16x16x32_bf16 v[62:65], v[144:147], v[176:179], v[62:65]
	v_mfma_f32_16x16x32_bf16 v[58:61], v[152:155], v[176:179], v[58:61]
	v_mfma_f32_16x16x32_bf16 v[54:57], v[144:147], v[184:187], v[54:57]
	v_mfma_f32_16x16x32_bf16 v[50:53], v[152:155], v[184:187], v[50:53]
	v_mfma_f32_16x16x32_bf16 v[38:41], v[144:147], v[192:195], v[38:41]
	v_mfma_f32_16x16x32_bf16 v[34:37], v[152:155], v[192:195], v[34:37]
	v_mfma_f32_16x16x32_bf16 v[22:25], v[144:147], v[200:203], v[22:25]
	v_mfma_f32_16x16x32_bf16 v[18:21], v[152:155], v[200:203], v[18:21]
	s_setprio 0
	s_setprio 1
	v_mfma_f32_16x16x32_bf16 v[46:49], v[156:159], v[172:175], 0
	v_mfma_f32_16x16x32_bf16 v[42:45], v[164:167], v[172:175], 0
	v_mfma_f32_16x16x32_bf16 v[30:33], v[156:159], v[180:183], 0
	v_mfma_f32_16x16x32_bf16 v[26:29], v[164:167], v[180:183], 0
	v_mfma_f32_16x16x32_bf16 v[14:17], v[156:159], v[188:191], 0
	v_mfma_f32_16x16x32_bf16 v[10:13], v[164:167], v[188:191], 0
	v_mfma_f32_16x16x32_bf16 v[6:9], v[156:159], v[196:199], 0
	v_mfma_f32_16x16x32_bf16 v[2:5], v[164:167], v[196:199], 0
	v_mfma_f32_16x16x32_bf16 v[46:49], v[160:163], v[176:179], v[46:49]
	v_mfma_f32_16x16x32_bf16 v[42:45], v[168:171], v[176:179], v[42:45]
	v_mfma_f32_16x16x32_bf16 v[30:33], v[160:163], v[184:187], v[30:33]
	v_mfma_f32_16x16x32_bf16 v[26:29], v[168:171], v[184:187], v[26:29]
	v_mfma_f32_16x16x32_bf16 v[14:17], v[160:163], v[192:195], v[14:17]
	v_mfma_f32_16x16x32_bf16 v[10:13], v[168:171], v[192:195], v[10:13]
	v_mfma_f32_16x16x32_bf16 v[6:9], v[160:163], v[200:203], v[6:9]
	v_mfma_f32_16x16x32_bf16 v[2:5], v[168:171], v[200:203], v[2:5]
	s_setprio 0
	s_barrier
	v_add_u32_e32 v152, 0x18000, v138
	v_add_u32_e32 v168, 0x1c000, v138
	ds_read_b128 v[140:143], v152
	ds_read_b128 v[144:147], v152 offset:1024
	ds_read_b128 v[148:151], v152 offset:2048
	ds_read_b128 v[152:155], v152 offset:3072
	ds_read_b128 v[156:159], v168
	ds_read_b128 v[160:163], v168 offset:1024
	ds_read_b128 v[164:167], v168 offset:2048
	ds_read_b128 v[168:171], v168 offset:3072
	s_mov_b32 m0, s45
	v_lshl_add_u64 v[208:209], v[206:207], 0, s[96:97]
	ds_read_b128 v[172:175], v139 offset:32768
	ds_read_b128 v[176:179], v139 offset:33792
	ds_read_b128 v[180:183], v139 offset:34816
	ds_read_b128 v[184:187], v139 offset:35840
	ds_read_b128 v[188:191], v139 offset:36864
	ds_read_b128 v[192:195], v139 offset:37888
	ds_read_b128 v[196:199], v139 offset:38912
	ds_read_b128 v[200:203], v139 offset:39936
	global_load_lds_dwordx4 v[208:209], off
	v_lshl_add_u64 v[208:209], v[206:207], 0, s[30:31]
	s_mov_b32 m0, s46
	s_nop 0
	global_load_lds_dwordx4 v[208:209], off
	s_waitcnt vmcnt(8)
	s_waitcnt lgkmcnt(0)
	s_barrier
	s_setprio 1
	s_waitcnt lgkmcnt(0)
	v_mfma_f32_16x16x32_bf16 v[128:131], v[140:143], v[172:175], v[128:131]
	v_mfma_f32_16x16x32_bf16 v[124:127], v[148:151], v[172:175], v[124:127]
	v_mfma_f32_16x16x32_bf16 v[120:123], v[140:143], v[180:183], v[120:123]
	v_mfma_f32_16x16x32_bf16 v[116:119], v[148:151], v[180:183], v[116:119]
	v_mfma_f32_16x16x32_bf16 v[104:107], v[140:143], v[188:191], v[104:107]
	v_mfma_f32_16x16x32_bf16 v[100:103], v[148:151], v[188:191], v[100:103]
	v_mfma_f32_16x16x32_bf16 v[88:91], v[140:143], v[196:199], v[88:91]
	v_mfma_f32_16x16x32_bf16 v[84:87], v[148:151], v[196:199], v[84:87]
	v_mfma_f32_16x16x32_bf16 v[128:131], v[144:147], v[176:179], v[128:131]
	v_mfma_f32_16x16x32_bf16 v[124:127], v[152:155], v[176:179], v[124:127]
	v_mfma_f32_16x16x32_bf16 v[120:123], v[144:147], v[184:187], v[120:123]
	v_mfma_f32_16x16x32_bf16 v[116:119], v[152:155], v[184:187], v[116:119]
	v_mfma_f32_16x16x32_bf16 v[104:107], v[144:147], v[192:195], v[104:107]
	v_mfma_f32_16x16x32_bf16 v[100:103], v[152:155], v[192:195], v[100:103]
	v_mfma_f32_16x16x32_bf16 v[88:91], v[144:147], v[200:203], v[88:91]
	v_mfma_f32_16x16x32_bf16 v[84:87], v[152:155], v[200:203], v[84:87]
	s_setprio 0
	s_setprio 1
	v_mfma_f32_16x16x32_bf16 v[112:115], v[156:159], v[172:175], v[112:115]
	v_mfma_f32_16x16x32_bf16 v[108:111], v[164:167], v[172:175], v[108:111]
	v_mfma_f32_16x16x32_bf16 v[96:99], v[156:159], v[180:183], v[96:99]
	v_mfma_f32_16x16x32_bf16 v[92:95], v[164:167], v[180:183], v[92:95]
	v_mfma_f32_16x16x32_bf16 v[80:83], v[156:159], v[188:191], v[80:83]
	v_mfma_f32_16x16x32_bf16 v[76:79], v[164:167], v[188:191], v[76:79]
	v_mfma_f32_16x16x32_bf16 v[72:75], v[156:159], v[196:199], v[72:75]
	v_mfma_f32_16x16x32_bf16 v[68:71], v[164:167], v[196:199], v[68:71]
	v_mfma_f32_16x16x32_bf16 v[112:115], v[160:163], v[176:179], v[112:115]
	v_mfma_f32_16x16x32_bf16 v[108:111], v[168:171], v[176:179], v[108:111]
	v_mfma_f32_16x16x32_bf16 v[96:99], v[160:163], v[184:187], v[96:99]
	v_mfma_f32_16x16x32_bf16 v[92:95], v[168:171], v[184:187], v[92:95]
	v_mfma_f32_16x16x32_bf16 v[80:83], v[160:163], v[192:195], v[80:83]
	v_mfma_f32_16x16x32_bf16 v[76:79], v[168:171], v[192:195], v[76:79]
	v_mfma_f32_16x16x32_bf16 v[72:75], v[160:163], v[200:203], v[72:75]
	v_mfma_f32_16x16x32_bf16 v[68:71], v[168:171], v[200:203], v[68:71]
	s_setprio 0
	s_barrier
; #define G_STAGE_B(bufoff, gbase) do { G_GLDS((const char*)(gbase) + voffB0, (bufoff) + ldsw); G_GLDS((const char*)(gbase) + vstep64 + voffB0, (bufoff) + ldsw + 8192); } while (0)
; #define G_STAGE_AU(bufoff, gbase) do { G_GLDS((const char*)(gbase) + voffA0, (bufoff) + ldsw); G_GLDS((const char*)(gbase) + vstep64 + voffA0, (bufoff) + ldsw + 8192); } while (0)
; #define X_LDA(b, h) do { if constexpr (MODE == 2) G_LDA8(A8, b, h); else G_LDA(At, b, h); } while (0)
; #define X_MMA0(ai, bj) do { if constexpr (MODE == 2) G_MMA8(ai, bj, A8, B08); else G_MMA(ai, bj, At, B0); } while (0)
; #define X_MMA1(ai, bj) do { if constexpr (MODE == 2) G_MMA8(ai, bj, A8, B18); else G_MMA(ai, bj, At, B1); } while (0)
; #define G_WAIT_V(n) asm volatile("s_waitcnt vmcnt(" #n ")" ::: "memory")
; #define G_WAIT_L(n) asm volatile("s_waitcnt lgkmcnt(" #n ")" ::: "memory")
; #define G_BAR __builtin_amdgcn_s_barrier()
; #define G_SCHED __builtin_amdgcn_sched_barrier(0)
;     ...
;             X_LDA(1, 1); G_STAGE_B(G_SB(1, 0), b3); G_STAGE_B(G_SB(1, 1), b3 + hstep); G_STAGE_AU(G_SA(1, 0), a3);
;             G_WAIT_V(8); G_WAIT_L(0); G_BAR; X_MMA0(1, 0); X_MMA1(1, 1); G_BAR; G_SCHED;
;         }
	s_mov_b32 m0, s47
	v_lshl_add_u64 v[208:209], v[204:205], 0, s[82:83]
	ds_read_b128 v[172:175], v139 offset:49152
	ds_read_b128 v[176:179], v139 offset:50176
	ds_read_b128 v[180:183], v139 offset:51200
	ds_read_b128 v[184:187], v139 offset:52224
	ds_read_b128 v[188:191], v139 offset:53248
	ds_read_b128 v[192:195], v139 offset:54272
	ds_read_b128 v[196:199], v139 offset:55296
	ds_read_b128 v[200:203], v139 offset:56320
	global_load_lds_dwordx4 v[208:209], off
	v_lshl_add_u64 v[208:209], v[204:205], 0, s[88:89]
	s_mov_b32 m0, s48
	s_nop 0
	global_load_lds_dwordx4 v[208:209], off
	v_lshl_add_u64 v[208:209], v[204:205], 0, s[66:67]
	s_mov_b32 m0, s51
	v_lshl_add_u64 v[204:205], v[204:205], 0, s[68:69]
	global_load_lds_dwordx4 v[208:209], off
	s_mov_b32 m0, s52
	s_nop 0
	global_load_lds_dwordx4 v[204:205], off
	v_lshl_add_u64 v[204:205], v[206:207], 0, s[82:83]
	s_mov_b32 m0, s49
	s_nop 0
	global_load_lds_dwordx4 v[204:205], off
	v_lshl_add_u64 v[204:205], v[206:207], 0, s[88:89]
	s_mov_b32 m0, s50
	s_nop 0
	global_load_lds_dwordx4 v[204:205], off
	s_waitcnt vmcnt(8)
	s_waitcnt lgkmcnt(0)
	s_barrier
	s_setprio 1
	s_waitcnt lgkmcnt(0)
	v_mfma_f32_16x16x32_bf16 v[62:65], v[140:143], v[172:175], v[62:65]
	v_mfma_f32_16x16x32_bf16 v[58:61], v[148:151], v[172:175], v[58:61]
	v_mfma_f32_16x16x32_bf16 v[54:57], v[140:143], v[180:183], v[54:57]
	v_mfma_f32_16x16x32_bf16 v[50:53], v[148:151], v[180:183], v[50:53]
	v_mfma_f32_16x16x32_bf16 v[38:41], v[140:143], v[188:191], v[38:41]
	v_mfma_f32_16x16x32_bf16 v[34:37], v[148:151], v[188:191], v[34:37]
	v_mfma_f32_16x16x32_bf16 v[22:25], v[140:143], v[196:199], v[22:25]
	v_mfma_f32_16x16x32_bf16 v[18:21], v[148:151], v[196:199], v[18:21]
	v_mfma_f32_16x16x32_bf16 v[62:65], v[144:147], v[176:179], v[62:65]
	v_mfma_f32_16x16x32_bf16 v[58:61], v[152:155], v[176:179], v[58:61]
	v_mfma_f32_16x16x32_bf16 v[54:57], v[144:147], v[184:187], v[54:57]
	v_mfma_f32_16x16x32_bf16 v[50:53], v[152:155], v[184:187], v[50:53]
	v_mfma_f32_16x16x32_bf16 v[38:41], v[144:147], v[192:195], v[38:41]
	v_mfma_f32_16x16x32_bf16 v[34:37], v[152:155], v[192:195], v[34:37]
	v_mfma_f32_16x16x32_bf16 v[22:25], v[144:147], v[200:203], v[22:25]
	v_mfma_f32_16x16x32_bf16 v[18:21], v[152:155], v[200:203], v[18:21]
	s_setprio 0
	s_setprio 1
	v_mfma_f32_16x16x32_bf16 v[46:49], v[156:159], v[172:175], v[46:49]
	v_mfma_f32_16x16x32_bf16 v[42:45], v[164:167], v[172:175], v[42:45]
	v_mfma_f32_16x16x32_bf16 v[30:33], v[156:159], v[180:183], v[30:33]
	v_mfma_f32_16x16x32_bf16 v[26:29], v[164:167], v[180:183], v[26:29]
	v_mfma_f32_16x16x32_bf16 v[14:17], v[156:159], v[188:191], v[14:17]
	v_mfma_f32_16x16x32_bf16 v[10:13], v[164:167], v[188:191], v[10:13]
	v_mfma_f32_16x16x32_bf16 v[6:9], v[156:159], v[196:199], v[6:9]
	v_mfma_f32_16x16x32_bf16 v[2:5], v[164:167], v[196:199], v[2:5]
	v_mfma_f32_16x16x32_bf16 v[46:49], v[160:163], v[176:179], v[46:49]
	v_mfma_f32_16x16x32_bf16 v[42:45], v[168:171], v[176:179], v[42:45]
	v_mfma_f32_16x16x32_bf16 v[30:33], v[160:163], v[184:187], v[30:33]
	v_mfma_f32_16x16x32_bf16 v[26:29], v[168:171], v[184:187], v[26:29]
	v_mfma_f32_16x16x32_bf16 v[14:17], v[160:163], v[192:195], v[14:17]
	v_mfma_f32_16x16x32_bf16 v[10:13], v[168:171], v[192:195], v[10:13]
	v_mfma_f32_16x16x32_bf16 v[6:9], v[160:163], v[200:203], v[6:9]
	v_mfma_f32_16x16x32_bf16 v[2:5], v[168:171], v[200:203], v[2:5]
	s_setprio 0
	s_barrier
	s_add_i32 s58, s58, 2
	s_add_u32 s40, s40, 0x100
	s_addc_u32 s41, s41, 0
	s_add_u32 s42, s42, 0x100
	s_addc_u32 s43, s43, 0
	s_cmp_gt_u32 s58, 13
	s_cbranch_scc1 .Lmy_peel_outproj_exit

; #define G_BAR __builtin_amdgcn_s_barrier()
;     ...
;         if (wr == 0) G_BAR;
.Lmy_peel_outproj_exit:
	s_and_b64 vcc, exec, s[8:9]
	s_cbranch_vccz .LBB0_710
	s_barrier

; #define LAS __attribute__((address_space(3)))
; #define G_STAGE_B(bufoff, gbase) do { G_GLDS((const char*)(gbase) + voffB0, (bufoff) + ldsw); G_GLDS((const char*)(gbase) + vstep64 + voffB0, (bufoff) + ldsw + 8192); } while (0)
; #define G_STAGE_A(bufoff, kofs, v0, v1) do { G_GLDS((const char*)A + (kofs) + (v0), (bufoff) + ldsw); G_GLDS((const char*)A + (kofs) + (v1), (bufoff) + ldsw + 8192); } while (0)
; #define G_WAIT_V(n) asm volatile("s_waitcnt vmcnt(" #n ")" ::: "memory")
; #define G_BAR __builtin_amdgcn_s_barrier()
; #define G_VOA(dst, u) do { _Pragma("unroll") for (int h = 0; h < 2; ++h) _Pragma("unroll") for (int i = 0; i < 2; ++i) dst[h][i] = (S.arow(u, h * HALF + R0 + 64 * i) * (unsigned)K + (unsigned)C0) * 2u; } while (0)
;     ...
; #pragma unroll
;     for (int a = 0; a < 2; ++a)
; #pragma unroll
;         for (int b = 0; b < 2; ++b)
; #pragma unroll
;             for (int m = 0; m < 4; ++m)
; #pragma unroll
;                 for (int n = 0; n < 2; ++n) acc[a][b][m][n] = (f32x4){0.f, 0.f, 0.f, 0.f};
;     bf16x8 At[4][2], B0[2][2], B1[2][2];
;     i32x8 A8[4], B08[2], B18[2];
;     const int scl8 = 0x7f7f7f7f;
;     const char* cB = (const char*)S.bbase(cur) + (size_t)cur.pn * tstep;
;     if constexpr (GATHER) {
;     unsigned vo[2][2];
;     LAS u32x4* nvo_l = (LAS u32x4*)(lds + NVO_OFF) + tid;
;     G_VOA(vo, cur);
;     G_STAGE_B(G_SB(0, 0), cB); G_STAGE_B(G_SB(0, 1), cB + hstep); G_STAGE_A(G_SA(0, 0), 0, vo[0][0], vo[0][1]); G_STAGE_A(G_SA(0, 1), 0, vo[1][0], vo[1][1]);
;     if (wr == 1) G_BAR;
;     G_WAIT_V(2); G_BAR;
;     G_STAGE_B(G_SB(1, 0), cB + kstep); G_STAGE_A(G_SA(1, 0), kstep, vo[0][0], vo[0][1]); G_STAGE_B(G_SB(1, 1), cB + hstep + kstep);
;     G_WAIT_V(6); G_BAR;
.LBB0_967:
	v_lshrrev_b32_e32 v10, 1, v4
	v_readlane_b32 s7, v255, 1
	v_and_b32_e32 v10, 24, v10
	v_and_b32_e32 v5, 15, v4
	v_lshl_add_u32 v206, v4, 4, s7
	v_lshlrev_b32_e32 v11, 1, v10
	v_lshlrev_b32_e32 v4, 2, v4
	v_lshl_or_b32 v207, s6, 6, v5
	v_lshl_or_b32 v5, v5, 6, v11
	s_lshl_b32 s6, s6, 13
	v_and_b32_e32 v4, 32, v4
	s_lshl_b32 s2, s2, 5
	v_bitop3_b32 v11, v5, s6, v4 bitop3:0xde
	s_and_b32 s6, s2, 0x60
	s_lshl_b32 s2, s6, 7
	v_bitop3_b32 v12, v5, s2, v4 bitop3:0xde
	s_add_i32 s2, s3, 0x18000
	v_lshl_add_u64 v[4:5], v[2:3], 0, s[82:83]
	s_mov_b32 m0, s2
	s_add_i32 s73, s3, 0x1a000
	v_readlane_b32 s10, v254, 53
	v_mov_b32_e32 v66, v34
	s_waitcnt vmcnt(2)
	s_barrier
	global_load_lds_dwordx4 v[4:5], off
	v_lshl_add_u64 v[4:5], v[2:3], 0, s[22:23]
	s_mov_b32 m0, s73
	v_readlane_b32 s11, v254, 54
	s_add_i32 s86, s3, 0x8000
	v_mov_b32_e32 v8, v35
	v_mov_b32_e32 v9, v67
	global_load_lds_dwordx4 v[4:5], off
	v_lshl_add_u64 v[4:5], s[10:11], 0, v[66:67]
	s_mov_b32 m0, s86
	s_add_i32 s90, s3, 0xa000
	global_load_lds_dwordx4 v[4:5], off
	v_lshl_add_u64 v[4:5], s[10:11], 0, v[8:9]
	s_mov_b32 m0, s90
	s_add_i32 s91, s3, 0x1c000
	global_load_lds_dwordx4 v[4:5], off
	v_lshl_add_u64 v[4:5], v[2:3], 0, s[88:89]
	s_mov_b32 m0, s91
	s_add_i32 s94, s3, 0x1e000
	global_load_lds_dwordx4 v[4:5], off
	v_lshl_add_u64 v[2:3], v[2:3], 0, s[74:75]
	s_mov_b32 m0, s94
	s_cmpk_lt_u32 s1, 0x100
	global_load_lds_dwordx4 v[2:3], off
	s_cselect_b64 s[10:11], -1, 0
	s_lshr_b32 s44, s65, 4
	v_cvt_f32_ubyte0_e32 v2, s44
	v_rcp_iflag_f32_e32 v2, v2
	s_ashr_i32 s1, s0, 31
	s_lshr_b32 s7, s1, 29
	s_add_i32 s7, s0, s7
	v_mul_f32_e32 v2, 0x4f7ffffe, v2
	v_cvt_u32_f32_e32 v2, v2
	s_ashr_i32 s95, s7, 3
	s_and_b32 s7, s7, -8
	s_sub_i32 s45, s0, s7
	v_or_b32_e32 v208, s6, v10
	s_sub_i32 s6, 0, s44
	v_readfirstlane_b32 s7, v2
	s_waitcnt vmcnt(6)
	s_mul_i32 s6, s6, s7
	s_mul_hi_u32 s6, s7, s6
	v_mov_b32_e32 v38, 0
	v_ashrrev_i32_e32 v169, 31, v168
	s_add_i32 s16, s95, 1
	s_mov_b32 s67, 0
	s_add_i32 s66, s7, s6
	v_add_u32_e32 v209, 0, v12
	v_add_u32_e32 v210, 0, v11
	v_mov_b32_e32 v172, v37
	v_mov_b32_e32 v174, v36
	s_barrier
	s_branch .LBB0_969

;     ...
;         if (!has_next) break;
; #pragma unroll
;         for (int a = 0; a < 2; ++a)
; #pragma unroll
;             for (int b = 0; b < 2; ++b)
; #pragma unroll
;                 for (int m = 0; m < 4; ++m)
; #pragma unroll
;                     for (int n = 0; n < 2; ++n) acc[a][b][m][n] = (f32x4){0.f, 0.f, 0.f, 0.f};
;         cur = nxt; cB = nB; ++ui;
;         { const u32x4 nv = *nvo_l; vo[0][0] = nv[0]; vo[0][1] = nv[1]; vo[1][0] = nv[2]; vo[1][1] = nv[3]; }
.Lmy_gu_zero_last:
	s_branch .LBB0_1003
.LBB0_994:
	v_add_u32_e32 v2, s58, v168
	v_add_u32_e32 v3, s58, v194
	v_add_u32_e32 v4, s58, v195
	v_add_u32_e32 v5, s58, v204

; #define G_STAGE_B(bufoff, gbase) do { G_GLDS((const char*)(gbase) + voffB0, (bufoff) + ldsw); G_GLDS((const char*)(gbase) + vstep64 + voffB0, (bufoff) + ldsw + 8192); } while (0)
; #define G_STAGE_A(bufoff, kofs, v0, v1) do { G_GLDS((const char*)A + (kofs) + (v0), (bufoff) + ldsw); G_GLDS((const char*)A + (kofs) + (v1), (bufoff) + ldsw + 8192); } while (0)
; #define X_LDA(b, h) do { if constexpr (MODE == 2) G_LDA8(A8, b, h); else G_LDA(At, b, h); } while (0)
; #define X_LDB0(b, h) do { if constexpr (MODE == 2) G_LDB8(B08, b, h); else G_LDB(B0, b, h); } while (0)
; #define X_LDB1(b, h) do { if constexpr (MODE == 2) G_LDB8(B18, b, h); else G_LDB(B1, b, h); } while (0)
; #define X_MMA0(ai, bj) do { if constexpr (MODE == 2) G_MMA8(ai, bj, A8, B08); else G_MMA(ai, bj, At, B0); } while (0)
; #define X_MMA1(ai, bj) do { if constexpr (MODE == 2) G_MMA8(ai, bj, A8, B18); else G_MMA(ai, bj, At, B1); } while (0)
; #define G_WAIT_V(n) asm volatile("s_waitcnt vmcnt(" #n ")" ::: "memory")
; #define G_WAIT_L(n) asm volatile("s_waitcnt lgkmcnt(" #n ")" ::: "memory")
; #define G_BAR __builtin_amdgcn_s_barrier()
; #define G_SCHED __builtin_amdgcn_sched_barrier(0)
;     ...
;         for (int t = 0; t < nt; t += 2) {
;             const bool last = (t == nt - 2);
;             const size_t k1 = (size_t)(t + 1) * kstep;
;             const size_t k2 = last ? 0 : (size_t)(t + 2) * kstep;
;             const char* b2 = last ? nB : cB + (size_t)(t + 2) * kstep;
;             const char* b3 = b2 + kstep;
;             unsigned w00 = vo[0][0], w01 = vo[0][1], w10 = vo[1][0], w11 = vo[1][1];
;             if (last) { const u32x4 nv = *nvo_l; w00 = nv[0]; w01 = nv[1]; w10 = nv[2]; w11 = nv[3]; }
;             X_LDB0(0, 0); X_LDB1(0, 1); G_SCHED; X_LDA(0, 0); G_STAGE_A(G_SA(1, 1), k1, vo[1][0], vo[1][1]);
;             G_WAIT_V(8); G_WAIT_L(0); G_BAR; X_MMA0(0, 0); X_MMA1(0, 1); G_BAR; G_SCHED;
;             X_LDA(0, 1); G_STAGE_B(G_SB(0, 0), b2); G_STAGE_B(G_SB(0, 1), b2 + hstep); G_STAGE_A(G_SA(0, 0), k2, w00, w01);
;             G_WAIT_V(8); G_WAIT_L(0); G_BAR; X_MMA0(1, 0); X_MMA1(1, 1); G_BAR; G_SCHED;
.Lmy_peel_gu_1006:
	v_lshl_add_u64 v[2:3], v[178:179], 0, s[42:43]
	v_cndmask_b32_e32 v188, v2, v176, vcc
	v_add_u32_e32 v2, 0x10000, v209
	v_add_u32_e32 v14, 0x14000, v209
	v_cndmask_b32_e32 v189, v3, v177, vcc
	ds_read_b128 v[18:21], v2
	ds_read_b128 v[22:25], v2 offset:1024
	ds_read_b128 v[26:29], v2 offset:2048
	ds_read_b128 v[30:33], v2 offset:3072
	ds_read_b128 v[2:5], v14
	ds_read_b128 v[6:9], v14 offset:1024
	ds_read_b128 v[10:13], v14 offset:2048
	ds_read_b128 v[14:17], v14 offset:3072
	s_add_u32 s12, s42, 0x100
	s_addc_u32 s13, s43, 0
	s_and_b64 s[24:25], vcc, exec
	s_cselect_b32 s24, 0, s12
	v_lshl_add_u64 v[192:193], v[182:183], 0, s[42:43]
	s_add_i32 m0, s3, 0xc000
	ds_read_b128 v[232:235], v210
	ds_read_b128 v[236:239], v210 offset:1024
	ds_read_b128 v[240:243], v210 offset:2048
	ds_read_b128 v[244:247], v210 offset:3072
	ds_read_b128 v[196:199], v210 offset:4096
	ds_read_b128 v[200:203], v210 offset:5120
	ds_read_b128 v[212:215], v210 offset:6144
	ds_read_b128 v[216:219], v210 offset:7168
	global_load_lds_dwordx4 v[192:193], off
	v_lshl_add_u64 v[192:193], v[180:181], 0, s[42:43]
	s_add_i32 m0, s3, 0xe000
	s_nop 0
	global_load_lds_dwordx4 v[192:193], off
	s_waitcnt vmcnt(8)
	s_waitcnt lgkmcnt(0)
	s_barrier
	s_setprio 1
	s_waitcnt lgkmcnt(0)
	v_mfma_scale_f32_16x16x128_f8f6f4 v[164:167], v[18:25], v[232:239], 0, v222, v222 op_sel_hi:[0,0,0]
	v_mfma_scale_f32_16x16x128_f8f6f4 v[160:163], v[26:33], v[232:239], 0, v222, v222 op_sel_hi:[0,0,0]
	v_mfma_scale_f32_16x16x128_f8f6f4 v[156:159], v[18:25], v[240:247], 0, v222, v222 op_sel_hi:[0,0,0]
	v_mfma_scale_f32_16x16x128_f8f6f4 v[152:155], v[26:33], v[240:247], 0, v222, v222 op_sel_hi:[0,0,0]
	v_mfma_scale_f32_16x16x128_f8f6f4 v[148:151], v[18:25], v[196:203], 0, v222, v222 op_sel_hi:[0,0,0]
	v_mfma_scale_f32_16x16x128_f8f6f4 v[144:147], v[26:33], v[196:203], 0, v222, v222 op_sel_hi:[0,0,0]
	v_mfma_scale_f32_16x16x128_f8f6f4 v[140:143], v[18:25], v[212:219], 0, v222, v222 op_sel_hi:[0,0,0]
	v_mfma_scale_f32_16x16x128_f8f6f4 v[136:139], v[26:33], v[212:219], 0, v222, v222 op_sel_hi:[0,0,0]
	s_setprio 0
	s_setprio 1
	v_mfma_scale_f32_16x16x128_f8f6f4 v[132:135], v[2:9], v[232:239], 0, v222, v222 op_sel_hi:[0,0,0]
	v_mfma_scale_f32_16x16x128_f8f6f4 v[128:131], v[10:17], v[232:239], 0, v222, v222 op_sel_hi:[0,0,0]
	v_mfma_scale_f32_16x16x128_f8f6f4 v[124:127], v[2:9], v[240:247], 0, v222, v222 op_sel_hi:[0,0,0]
	v_mfma_scale_f32_16x16x128_f8f6f4 v[120:123], v[10:17], v[240:247], 0, v222, v222 op_sel_hi:[0,0,0]
	v_mfma_scale_f32_16x16x128_f8f6f4 v[116:119], v[2:9], v[196:203], 0, v222, v222 op_sel_hi:[0,0,0]
	v_mfma_scale_f32_16x16x128_f8f6f4 v[112:115], v[10:17], v[196:203], 0, v222, v222 op_sel_hi:[0,0,0]
	v_mfma_scale_f32_16x16x128_f8f6f4 v[108:111], v[2:9], v[212:219], 0, v222, v222 op_sel_hi:[0,0,0]
	v_mfma_scale_f32_16x16x128_f8f6f4 v[104:107], v[10:17], v[212:219], 0, v222, v222 op_sel_hi:[0,0,0]
	s_setprio 0
	s_barrier
	s_mov_b32 m0, s27
	v_lshl_add_u64 v[188:189], v[188:189], 0, v[170:171]
	ds_read_b128 v[196:199], v210 offset:16384
	ds_read_b128 v[200:203], v210 offset:17408
	ds_read_b128 v[212:215], v210 offset:18432
	ds_read_b128 v[216:219], v210 offset:19456
	ds_read_b128 v[232:235], v210 offset:20480
	ds_read_b128 v[236:239], v210 offset:21504
	ds_read_b128 v[240:243], v210 offset:22528
	ds_read_b128 v[244:247], v210 offset:23552
	global_load_lds_dwordx4 v[188:189], off
	v_lshl_add_u64 v[192:193], v[188:189], 0, s[20:21]
	s_mov_b32 m0, s28
	s_add_u32 s42, s78, s24
	global_load_lds_dwordx4 v[192:193], off
	v_lshl_add_u64 v[192:193], v[188:189], 0, s[18:19]
	s_mov_b32 m0, s29
	s_addc_u32 s43, s79, 0
	global_load_lds_dwordx4 v[192:193], off
	v_lshl_add_u64 v[192:193], v[188:189], 0, s[92:93]
	s_mov_b32 m0, s51
	v_mov_b32_e32 v191, v67
	global_load_lds_dwordx4 v[192:193], off
	s_mov_b32 m0, s3
	v_lshl_add_u64 v[192:193], s[42:43], 0, v[66:67]
	global_load_lds_dwordx4 v66, s[42:43]
	s_mov_b32 m0, s68
	s_nop 0
	global_load_lds_dwordx4 v190, s[42:43]
	s_waitcnt vmcnt(8)
	s_waitcnt lgkmcnt(0)
	v_lshl_add_u64 v[190:191], s[42:43], 0, v[190:191]
	s_barrier
	s_setprio 1
	s_waitcnt lgkmcnt(0)
	v_mfma_scale_f32_16x16x128_f8f6f4 v[100:103], v[18:25], v[196:203], 0, v222, v222 op_sel_hi:[0,0,0]
	v_mfma_scale_f32_16x16x128_f8f6f4 v[96:99], v[26:33], v[196:203], 0, v222, v222 op_sel_hi:[0,0,0]
	v_mfma_scale_f32_16x16x128_f8f6f4 v[92:95], v[18:25], v[212:219], 0, v222, v222 op_sel_hi:[0,0,0]
	v_mfma_scale_f32_16x16x128_f8f6f4 v[88:91], v[26:33], v[212:219], 0, v222, v222 op_sel_hi:[0,0,0]
	v_mfma_scale_f32_16x16x128_f8f6f4 v[84:87], v[18:25], v[232:239], 0, v222, v222 op_sel_hi:[0,0,0]
	v_mfma_scale_f32_16x16x128_f8f6f4 v[80:83], v[26:33], v[232:239], 0, v222, v222 op_sel_hi:[0,0,0]
	v_mfma_scale_f32_16x16x128_f8f6f4 v[76:79], v[18:25], v[240:247], 0, v222, v222 op_sel_hi:[0,0,0]
	v_mfma_scale_f32_16x16x128_f8f6f4 v[72:75], v[26:33], v[240:247], 0, v222, v222 op_sel_hi:[0,0,0]
	s_setprio 0
	s_setprio 1
	v_mfma_scale_f32_16x16x128_f8f6f4 v[68:71], v[2:9], v[196:203], 0, v222, v222 op_sel_hi:[0,0,0]
	v_mfma_scale_f32_16x16x128_f8f6f4 v[62:65], v[10:17], v[196:203], 0, v222, v222 op_sel_hi:[0,0,0]
	v_mfma_scale_f32_16x16x128_f8f6f4 v[58:61], v[2:9], v[212:219], 0, v222, v222 op_sel_hi:[0,0,0]
	v_mfma_scale_f32_16x16x128_f8f6f4 v[54:57], v[10:17], v[212:219], 0, v222, v222 op_sel_hi:[0,0,0]
	v_mfma_scale_f32_16x16x128_f8f6f4 v[50:53], v[2:9], v[232:239], 0, v222, v222 op_sel_hi:[0,0,0]
	v_mfma_scale_f32_16x16x128_f8f6f4 v[46:49], v[10:17], v[232:239], 0, v222, v222 op_sel_hi:[0,0,0]
	v_mfma_scale_f32_16x16x128_f8f6f4 v[42:45], v[2:9], v[240:247], 0, v222, v222 op_sel_hi:[0,0,0]
	v_mfma_scale_f32_16x16x128_f8f6f4 v[38:41], v[10:17], v[240:247], 0, v222, v222 op_sel_hi:[0,0,0]
	s_setprio 0
	s_barrier
; #define G_STAGE_B(bufoff, gbase) do { G_GLDS((const char*)(gbase) + voffB0, (bufoff) + ldsw); G_GLDS((const char*)(gbase) + vstep64 + voffB0, (bufoff) + ldsw + 8192); } while (0)
; #define G_STAGE_A(bufoff, kofs, v0, v1) do { G_GLDS((const char*)A + (kofs) + (v0), (bufoff) + ldsw); G_GLDS((const char*)A + (kofs) + (v1), (bufoff) + ldsw + 8192); } while (0)
; #define X_LDA(b, h) do { if constexpr (MODE == 2) G_LDA8(A8, b, h); else G_LDA(At, b, h); } while (0)
; #define X_LDB0(b, h) do { if constexpr (MODE == 2) G_LDB8(B08, b, h); else G_LDB(B0, b, h); } while (0)
; #define X_LDB1(b, h) do { if constexpr (MODE == 2) G_LDB8(B18, b, h); else G_LDB(B1, b, h); } while (0)
; #define X_MMA0(ai, bj) do { if constexpr (MODE == 2) G_MMA8(ai, bj, A8, B08); else G_MMA(ai, bj, At, B0); } while (0)
; #define X_MMA1(ai, bj) do { if constexpr (MODE == 2) G_MMA8(ai, bj, A8, B18); else G_MMA(ai, bj, At, B1); } while (0)
; #define G_WAIT_V(n) asm volatile("s_waitcnt vmcnt(" #n ")" ::: "memory")
; #define G_WAIT_L(n) asm volatile("s_waitcnt lgkmcnt(" #n ")" ::: "memory")
; #define G_BAR __builtin_amdgcn_s_barrier()
; #define G_SCHED __builtin_amdgcn_sched_barrier(0)
;     ...
;             X_LDB0(1, 0); X_LDB1(1, 1); G_SCHED; X_LDA(1, 0); G_STAGE_A(G_SA(0, 1), k2, w10, w11);
;             G_WAIT_V(8); G_WAIT_L(0); G_BAR; X_MMA0(0, 0); X_MMA1(0, 1); G_BAR; G_SCHED;
;             X_LDA(1, 1); G_STAGE_B(G_SB(1, 0), b3); G_STAGE_B(G_SB(1, 1), b3 + hstep); G_STAGE_A(G_SA(1, 0), k2 + kstep, w00, w01);
;             G_WAIT_V(8); G_WAIT_L(0); G_BAR; X_MMA0(1, 0); X_MMA1(1, 1); G_BAR; G_SCHED;
	v_add_u32_e32 v14, 0x18000, v209
	v_add_u32_e32 v30, 0x1c000, v209
	ds_read_b128 v[2:5], v14
	ds_read_b128 v[6:9], v14 offset:1024
	ds_read_b128 v[10:13], v14 offset:2048
	ds_read_b128 v[14:17], v14 offset:3072
	ds_read_b128 v[18:21], v30
	ds_read_b128 v[22:25], v30 offset:1024
	ds_read_b128 v[26:29], v30 offset:2048
	ds_read_b128 v[30:33], v30 offset:3072
	s_mov_b32 m0, s69
	v_lshl_add_u64 v[186:187], s[42:43], 0, v[186:187]
	ds_read_b128 v[196:199], v210 offset:32768
	ds_read_b128 v[200:203], v210 offset:33792
	ds_read_b128 v[212:215], v210 offset:34816
	ds_read_b128 v[216:219], v210 offset:35840
	ds_read_b128 v[232:235], v210 offset:36864
	ds_read_b128 v[236:239], v210 offset:37888
	ds_read_b128 v[240:243], v210 offset:38912
	ds_read_b128 v[244:247], v210 offset:39936
	global_load_lds_dwordx4 v[186:187], off
	v_lshl_add_u64 v[184:185], s[42:43], 0, v[184:185]
	s_mov_b32 m0, s72
	s_nop 0
	global_load_lds_dwordx4 v[184:185], off
	s_waitcnt vmcnt(8)
	s_waitcnt lgkmcnt(0)
	s_barrier
	s_setprio 1
	s_waitcnt lgkmcnt(0)
	v_mfma_scale_f32_16x16x128_f8f6f4 v[164:167], v[2:9], v[196:203], v[164:167], v222, v222 op_sel_hi:[0,0,0]
	v_mfma_scale_f32_16x16x128_f8f6f4 v[160:163], v[10:17], v[196:203], v[160:163], v222, v222 op_sel_hi:[0,0,0]
	v_mfma_scale_f32_16x16x128_f8f6f4 v[156:159], v[2:9], v[212:219], v[156:159], v222, v222 op_sel_hi:[0,0,0]
	v_mfma_scale_f32_16x16x128_f8f6f4 v[152:155], v[10:17], v[212:219], v[152:155], v222, v222 op_sel_hi:[0,0,0]
	v_mfma_scale_f32_16x16x128_f8f6f4 v[148:151], v[2:9], v[232:239], v[148:151], v222, v222 op_sel_hi:[0,0,0]
	v_mfma_scale_f32_16x16x128_f8f6f4 v[144:147], v[10:17], v[232:239], v[144:147], v222, v222 op_sel_hi:[0,0,0]
	v_mfma_scale_f32_16x16x128_f8f6f4 v[140:143], v[2:9], v[240:247], v[140:143], v222, v222 op_sel_hi:[0,0,0]
	v_mfma_scale_f32_16x16x128_f8f6f4 v[136:139], v[10:17], v[240:247], v[136:139], v222, v222 op_sel_hi:[0,0,0]
	s_setprio 0
	s_setprio 1
	v_mfma_scale_f32_16x16x128_f8f6f4 v[132:135], v[18:25], v[196:203], v[132:135], v222, v222 op_sel_hi:[0,0,0]
	v_mfma_scale_f32_16x16x128_f8f6f4 v[128:131], v[26:33], v[196:203], v[128:131], v222, v222 op_sel_hi:[0,0,0]
	v_mfma_scale_f32_16x16x128_f8f6f4 v[124:127], v[18:25], v[212:219], v[124:127], v222, v222 op_sel_hi:[0,0,0]
	v_mfma_scale_f32_16x16x128_f8f6f4 v[120:123], v[26:33], v[212:219], v[120:123], v222, v222 op_sel_hi:[0,0,0]
	v_mfma_scale_f32_16x16x128_f8f6f4 v[116:119], v[18:25], v[232:239], v[116:119], v222, v222 op_sel_hi:[0,0,0]
	v_mfma_scale_f32_16x16x128_f8f6f4 v[112:115], v[26:33], v[232:239], v[112:115], v222, v222 op_sel_hi:[0,0,0]
	v_mfma_scale_f32_16x16x128_f8f6f4 v[108:111], v[18:25], v[240:247], v[108:111], v222, v222 op_sel_hi:[0,0,0]
	v_mfma_scale_f32_16x16x128_f8f6f4 v[104:107], v[26:33], v[240:247], v[104:107], v222, v222 op_sel_hi:[0,0,0]
	s_setprio 0
	s_barrier
	s_mov_b32 m0, s2
	v_lshl_add_u64 v[184:185], v[188:189], 0, s[82:83]
	ds_read_b128 v[196:199], v210 offset:49152
	ds_read_b128 v[200:203], v210 offset:50176
	ds_read_b128 v[212:215], v210 offset:51200
	ds_read_b128 v[216:219], v210 offset:52224
	ds_read_b128 v[232:235], v210 offset:53248
	ds_read_b128 v[236:239], v210 offset:54272
	ds_read_b128 v[240:243], v210 offset:55296
	ds_read_b128 v[244:247], v210 offset:56320
	global_load_lds_dwordx4 v[184:185], off
	v_lshl_add_u64 v[184:185], v[188:189], 0, s[22:23]
	s_mov_b32 m0, s73
	s_nop 0
	global_load_lds_dwordx4 v[184:185], off
	v_lshl_add_u64 v[184:185], v[188:189], 0, s[88:89]
	s_mov_b32 m0, s91
	s_nop 0
	global_load_lds_dwordx4 v[184:185], off
	v_lshl_add_u64 v[184:185], v[188:189], 0, s[74:75]
	s_mov_b32 m0, s94
	s_nop 0
	global_load_lds_dwordx4 v[184:185], off
	v_lshl_add_u64 v[184:185], v[192:193], 0, s[82:83]
	s_mov_b32 m0, s86
	s_nop 0
	global_load_lds_dwordx4 v[184:185], off
	v_lshl_add_u64 v[184:185], v[190:191], 0, s[82:83]
	s_mov_b32 m0, s90
	s_nop 0
	global_load_lds_dwordx4 v[184:185], off
	s_waitcnt vmcnt(8)
	s_waitcnt lgkmcnt(0)
	s_barrier
	s_setprio 1
	s_waitcnt lgkmcnt(0)
	v_mfma_scale_f32_16x16x128_f8f6f4 v[100:103], v[2:9], v[196:203], v[100:103], v222, v222 op_sel_hi:[0,0,0]
	v_mfma_scale_f32_16x16x128_f8f6f4 v[96:99], v[10:17], v[196:203], v[96:99], v222, v222 op_sel_hi:[0,0,0]
	v_mfma_scale_f32_16x16x128_f8f6f4 v[92:95], v[2:9], v[212:219], v[92:95], v222, v222 op_sel_hi:[0,0,0]
	v_mfma_scale_f32_16x16x128_f8f6f4 v[88:91], v[10:17], v[212:219], v[88:91], v222, v222 op_sel_hi:[0,0,0]
	v_mfma_scale_f32_16x16x128_f8f6f4 v[84:87], v[2:9], v[232:239], v[84:87], v222, v222 op_sel_hi:[0,0,0]
	v_mfma_scale_f32_16x16x128_f8f6f4 v[80:83], v[10:17], v[232:239], v[80:83], v222, v222 op_sel_hi:[0,0,0]
	v_mfma_scale_f32_16x16x128_f8f6f4 v[76:79], v[2:9], v[240:247], v[76:79], v222, v222 op_sel_hi:[0,0,0]
	v_mfma_scale_f32_16x16x128_f8f6f4 v[72:75], v[10:17], v[240:247], v[72:75], v222, v222 op_sel_hi:[0,0,0]
	s_setprio 0
	s_setprio 1
	v_mfma_scale_f32_16x16x128_f8f6f4 v[68:71], v[18:25], v[196:203], v[68:71], v222, v222 op_sel_hi:[0,0,0]
	v_mfma_scale_f32_16x16x128_f8f6f4 v[62:65], v[26:33], v[196:203], v[62:65], v222, v222 op_sel_hi:[0,0,0]
	v_mfma_scale_f32_16x16x128_f8f6f4 v[58:61], v[18:25], v[212:219], v[58:61], v222, v222 op_sel_hi:[0,0,0]
	v_mfma_scale_f32_16x16x128_f8f6f4 v[54:57], v[26:33], v[212:219], v[54:57], v222, v222 op_sel_hi:[0,0,0]
	v_mfma_scale_f32_16x16x128_f8f6f4 v[50:53], v[18:25], v[232:239], v[50:53], v222, v222 op_sel_hi:[0,0,0]
	v_mfma_scale_f32_16x16x128_f8f6f4 v[46:49], v[26:33], v[232:239], v[46:49], v222, v222 op_sel_hi:[0,0,0]
	v_mfma_scale_f32_16x16x128_f8f6f4 v[42:45], v[18:25], v[240:247], v[42:45], v222, v222 op_sel_hi:[0,0,0]
	v_mfma_scale_f32_16x16x128_f8f6f4 v[38:41], v[26:33], v[240:247], v[38:41], v222, v222 op_sel_hi:[0,0,0]
	s_setprio 0
	s_barrier
	s_add_i32 s7, s7, 2
	s_cmp_gt_u32 s7, 5
	s_cbranch_scc1 .LBB0_1008
	s_mov_b64 s[42:43], s[12:13]

; #define G_STAGE_B(bufoff, gbase) do { G_GLDS((const char*)(gbase) + voffB0, (bufoff) + ldsw); G_GLDS((const char*)(gbase) + vstep64 + voffB0, (bufoff) + ldsw + 8192); } while (0)
; #define G_STAGE_AU(bufoff, gbase) do { G_GLDS((const char*)(gbase) + voffA0, (bufoff) + ldsw); G_GLDS((const char*)(gbase) + vstep64 + voffA0, (bufoff) + ldsw + 8192); } while (0)
; #define X_LDA(b, h) do { if constexpr (MODE == 2) G_LDA8(A8, b, h); else G_LDA(At, b, h); } while (0)
; #define X_LDB0(b, h) do { if constexpr (MODE == 2) G_LDB8(B08, b, h); else G_LDB(B0, b, h); } while (0)
; #define X_LDB1(b, h) do { if constexpr (MODE == 2) G_LDB8(B18, b, h); else G_LDB(B1, b, h); } while (0)
; #define X_MMA0(ai, bj) do { if constexpr (MODE == 2) G_MMA8(ai, bj, A8, B08); else G_MMA(ai, bj, At, B0); } while (0)
; #define X_MMA1(ai, bj) do { if constexpr (MODE == 2) G_MMA8(ai, bj, A8, B18); else G_MMA(ai, bj, At, B1); } while (0)
; #define G_WAIT_V(n) asm volatile("s_waitcnt vmcnt(" #n ")" ::: "memory")
; #define G_WAIT_L(n) asm volatile("s_waitcnt lgkmcnt(" #n ")" ::: "memory")
; #define G_BAR __builtin_amdgcn_s_barrier()
; #define G_SCHED __builtin_amdgcn_sched_barrier(0)
;     ...
;         for (int t = 0; t < nt; t += 2) {
;             const bool last = (t == nt - 2);
;             const char* a1 = cA + (size_t)(t + 1) * kstep;
;             const char* a2 = last ? nA : cA + (size_t)(t + 2) * kstep; const char* b2 = last ? nB : cB + (size_t)(t + 2) * kstep;
;             const char* a3 = a2 + kstep; const char* b3 = b2 + kstep;
;             X_LDB0(0, 0); X_LDB1(0, 1); G_SCHED; X_LDA(0, 0); G_STAGE_AU(G_SA(1, 1), a1 + hstep);
;             G_WAIT_V(8); G_WAIT_L(0); G_BAR; X_MMA0(0, 0); X_MMA1(0, 1); G_BAR; G_SCHED;
;             X_LDA(0, 1); G_STAGE_B(G_SB(0, 0), b2); G_STAGE_B(G_SB(0, 1), b2 + hstep); G_STAGE_AU(G_SA(0, 0), a2);
;             G_WAIT_V(8); G_WAIT_L(0); G_BAR; X_MMA0(1, 0); X_MMA1(1, 1); G_BAR; G_SCHED;
;     ...
; #pragma unroll
;         for (int a = 0; a < 2; ++a)
; #pragma unroll
;             for (int b = 0; b < 2; ++b)
; #pragma unroll
;                 for (int m = 0; m < 4; ++m)
; #pragma unroll
;                     for (int n = 0; n < 2; ++n) acc[a][b][m][n] = (f32x4){0.f, 0.f, 0.f, 0.f};
;         cur = nxt; cA = nA; cB = nB; ++ui;
.LBB0_1095:
	s_add_u32 s50, s50, 0x80
	s_addc_u32 s51, s51, 0
	s_add_u32 s11, s52, 0x100
	v_mov_b32_e32 v34, 0
	s_addc_u32 s13, s53, 0
	s_mov_b32 s25, 0
	s_waitcnt lgkmcnt(0)
.Lmy_peel_dn_1096:
	v_add_u32_e32 v2, 0x10000, v194
	v_add_u32_e32 v14, 0x14000, v194
	ds_read_b128 v[18:21], v2
	ds_read_b128 v[22:25], v2 offset:1024
	ds_read_b128 v[26:29], v2 offset:2048
	ds_read_b128 v[30:33], v2 offset:3072
	ds_read_b128 v[2:5], v14
	ds_read_b128 v[6:9], v14 offset:1024
	ds_read_b128 v[10:13], v14 offset:2048
	ds_read_b128 v[14:17], v14 offset:3072
	s_add_i32 s24, s25, 2
	s_add_u32 s52, s50, 0x80
	s_addc_u32 s53, s51, 0
	s_cmp_eq_u32 s65, s25
	s_cselect_b32 s53, s39, s53
	s_cselect_b32 s52, s38, s52
	s_cselect_b32 s55, s49, s13
	s_cselect_b32 s54, s48, s11
	v_lshl_add_u64 v[182:183], s[50:51], 0, v[170:171]
	s_add_i32 m0, s44, 0xc000
	ds_read_b128 v[174:177], v195
	ds_read_b128 v[178:181], v195 offset:1024
	ds_read_b128 v[196:199], v195 offset:2048
	ds_read_b128 v[200:203], v195 offset:3072
	ds_read_b128 v[204:207], v195 offset:4096
	ds_read_b128 v[208:211], v195 offset:5120
	ds_read_b128 v[212:215], v195 offset:6144
	ds_read_b128 v[216:219], v195 offset:7168
	global_load_lds_dwordx4 v[182:183], off
	v_lshl_add_u64 v[182:183], s[50:51], 0, v[172:173]
	s_add_i32 m0, s44, 0xe000
	s_nop 0
	global_load_lds_dwordx4 v[182:183], off
	s_waitcnt vmcnt(8)
	s_waitcnt lgkmcnt(0)
	s_barrier
	s_setprio 1
	s_waitcnt lgkmcnt(0)
	v_mfma_scale_f32_16x16x128_f8f6f4 v[160:163], v[18:25], v[174:181], 0, v222, v222 op_sel_hi:[0,0,0]
	v_mfma_scale_f32_16x16x128_f8f6f4 v[156:159], v[26:33], v[174:181], 0, v222, v222 op_sel_hi:[0,0,0]
	v_mfma_scale_f32_16x16x128_f8f6f4 v[144:147], v[18:25], v[196:203], 0, v222, v222 op_sel_hi:[0,0,0]
	v_mfma_scale_f32_16x16x128_f8f6f4 v[140:143], v[26:33], v[196:203], 0, v222, v222 op_sel_hi:[0,0,0]
	v_mfma_scale_f32_16x16x128_f8f6f4 v[128:131], v[18:25], v[204:211], 0, v222, v222 op_sel_hi:[0,0,0]
	v_mfma_scale_f32_16x16x128_f8f6f4 v[124:127], v[26:33], v[204:211], 0, v222, v222 op_sel_hi:[0,0,0]
	v_mfma_scale_f32_16x16x128_f8f6f4 v[112:115], v[18:25], v[212:219], 0, v222, v222 op_sel_hi:[0,0,0]
	v_mfma_scale_f32_16x16x128_f8f6f4 v[108:111], v[26:33], v[212:219], 0, v222, v222 op_sel_hi:[0,0,0]
	s_setprio 0
	s_setprio 1
	v_mfma_scale_f32_16x16x128_f8f6f4 v[152:155], v[2:9], v[174:181], 0, v222, v222 op_sel_hi:[0,0,0]
	v_mfma_scale_f32_16x16x128_f8f6f4 v[148:151], v[10:17], v[174:181], 0, v222, v222 op_sel_hi:[0,0,0]
	v_mfma_scale_f32_16x16x128_f8f6f4 v[136:139], v[2:9], v[196:203], 0, v222, v222 op_sel_hi:[0,0,0]
	v_mfma_scale_f32_16x16x128_f8f6f4 v[132:135], v[10:17], v[196:203], 0, v222, v222 op_sel_hi:[0,0,0]
	v_mfma_scale_f32_16x16x128_f8f6f4 v[120:123], v[2:9], v[204:211], 0, v222, v222 op_sel_hi:[0,0,0]
	v_mfma_scale_f32_16x16x128_f8f6f4 v[116:119], v[10:17], v[204:211], 0, v222, v222 op_sel_hi:[0,0,0]
	v_mfma_scale_f32_16x16x128_f8f6f4 v[104:107], v[2:9], v[212:219], 0, v222, v222 op_sel_hi:[0,0,0]
	v_mfma_scale_f32_16x16x128_f8f6f4 v[100:103], v[10:17], v[212:219], 0, v222, v222 op_sel_hi:[0,0,0]
	s_setprio 0
	s_barrier
	s_add_u32 s58, s54, s3
	s_addc_u32 s59, s55, 0
	v_lshl_add_u64 v[174:175], s[54:55], 0, v[164:165]
	s_add_u32 s54, s54, s16
	s_mov_b32 m0, s45
	s_addc_u32 s55, s55, 0
	ds_read_b128 v[196:199], v195 offset:16384
	ds_read_b128 v[200:203], v195 offset:17408
	ds_read_b128 v[204:207], v195 offset:18432
	ds_read_b128 v[208:211], v195 offset:19456
	ds_read_b128 v[212:215], v195 offset:20480
	ds_read_b128 v[216:219], v195 offset:21504
	ds_read_b128 v[232:235], v195 offset:22528
	ds_read_b128 v[236:239], v195 offset:23552
	global_load_lds_dwordx4 v[174:175], off
	v_lshl_add_u64 v[176:177], s[58:59], 0, v[164:165]
	s_mov_b32 m0, s66
	v_lshl_add_u64 v[178:179], s[54:55], 0, v[164:165]
	s_add_u32 s54, s54, s3
	global_load_lds_dwordx4 v[176:177], off
	s_mov_b32 m0, s67
	s_addc_u32 s55, s55, 0
	global_load_lds_dwordx4 v[178:179], off
	v_lshl_add_u64 v[180:181], s[54:55], 0, v[164:165]
	s_mov_b32 m0, s68
	s_add_u32 s54, s52, s3
	global_load_lds_dwordx4 v[180:181], off
	v_lshl_add_u64 v[182:183], s[52:53], 0, v[166:167]
	s_mov_b32 m0, s44
	s_addc_u32 s55, s53, 0
	global_load_lds_dwordx4 v[182:183], off
	v_lshl_add_u64 v[184:185], s[54:55], 0, v[166:167]
	s_mov_b32 m0, s69
	s_nop 0
	global_load_lds_dwordx4 v[184:185], off
	s_waitcnt vmcnt(8)
	s_waitcnt lgkmcnt(0)
	s_barrier
	s_setprio 1
	s_waitcnt lgkmcnt(0)
	v_mfma_scale_f32_16x16x128_f8f6f4 v[96:99], v[18:25], v[196:203], 0, v222, v222 op_sel_hi:[0,0,0]
	v_mfma_scale_f32_16x16x128_f8f6f4 v[92:95], v[26:33], v[196:203], 0, v222, v222 op_sel_hi:[0,0,0]
	v_mfma_scale_f32_16x16x128_f8f6f4 v[80:83], v[18:25], v[204:211], 0, v222, v222 op_sel_hi:[0,0,0]
	v_mfma_scale_f32_16x16x128_f8f6f4 v[76:79], v[26:33], v[204:211], 0, v222, v222 op_sel_hi:[0,0,0]
	v_mfma_scale_f32_16x16x128_f8f6f4 v[62:65], v[18:25], v[212:219], 0, v222, v222 op_sel_hi:[0,0,0]
	v_mfma_scale_f32_16x16x128_f8f6f4 v[58:61], v[26:33], v[212:219], 0, v222, v222 op_sel_hi:[0,0,0]
	v_mfma_scale_f32_16x16x128_f8f6f4 v[46:49], v[18:25], v[232:239], 0, v222, v222 op_sel_hi:[0,0,0]
	v_mfma_scale_f32_16x16x128_f8f6f4 v[42:45], v[26:33], v[232:239], 0, v222, v222 op_sel_hi:[0,0,0]
	s_setprio 0
	s_setprio 1
	v_mfma_scale_f32_16x16x128_f8f6f4 v[88:91], v[2:9], v[196:203], 0, v222, v222 op_sel_hi:[0,0,0]
	v_mfma_scale_f32_16x16x128_f8f6f4 v[84:87], v[10:17], v[196:203], 0, v222, v222 op_sel_hi:[0,0,0]
	v_mfma_scale_f32_16x16x128_f8f6f4 v[72:75], v[2:9], v[204:211], 0, v222, v222 op_sel_hi:[0,0,0]
	v_mfma_scale_f32_16x16x128_f8f6f4 v[68:71], v[10:17], v[204:211], 0, v222, v222 op_sel_hi:[0,0,0]
	v_mfma_scale_f32_16x16x128_f8f6f4 v[54:57], v[2:9], v[212:219], 0, v222, v222 op_sel_hi:[0,0,0]
	v_mfma_scale_f32_16x16x128_f8f6f4 v[50:53], v[10:17], v[212:219], 0, v222, v222 op_sel_hi:[0,0,0]
	v_mfma_scale_f32_16x16x128_f8f6f4 v[38:41], v[2:9], v[232:239], 0, v222, v222 op_sel_hi:[0,0,0]
	v_mfma_scale_f32_16x16x128_f8f6f4 v[34:37], v[10:17], v[232:239], 0, v222, v222 op_sel_hi:[0,0,0]
	s_setprio 0
	s_barrier
; #define G_STAGE_B(bufoff, gbase) do { G_GLDS((const char*)(gbase) + voffB0, (bufoff) + ldsw); G_GLDS((const char*)(gbase) + vstep64 + voffB0, (bufoff) + ldsw + 8192); } while (0)
; #define G_STAGE_AU(bufoff, gbase) do { G_GLDS((const char*)(gbase) + voffA0, (bufoff) + ldsw); G_GLDS((const char*)(gbase) + vstep64 + voffA0, (bufoff) + ldsw + 8192); } while (0)
; #define X_LDA(b, h) do { if constexpr (MODE == 2) G_LDA8(A8, b, h); else G_LDA(At, b, h); } while (0)
; #define X_LDB0(b, h) do { if constexpr (MODE == 2) G_LDB8(B08, b, h); else G_LDB(B0, b, h); } while (0)
; #define X_LDB1(b, h) do { if constexpr (MODE == 2) G_LDB8(B18, b, h); else G_LDB(B1, b, h); } while (0)
; #define X_MMA0(ai, bj) do { if constexpr (MODE == 2) G_MMA8(ai, bj, A8, B08); else G_MMA(ai, bj, At, B0); } while (0)
; #define X_MMA1(ai, bj) do { if constexpr (MODE == 2) G_MMA8(ai, bj, A8, B18); else G_MMA(ai, bj, At, B1); } while (0)
; #define G_WAIT_V(n) asm volatile("s_waitcnt vmcnt(" #n ")" ::: "memory")
; #define G_WAIT_L(n) asm volatile("s_waitcnt lgkmcnt(" #n ")" ::: "memory")
; #define G_BAR __builtin_amdgcn_s_barrier()
; #define G_SCHED __builtin_amdgcn_sched_barrier(0)
;     ...
;             X_LDB0(1, 0); X_LDB1(1, 1); G_SCHED; X_LDA(1, 0); G_STAGE_AU(G_SA(0, 1), a2 + hstep);
;             G_WAIT_V(8); G_WAIT_L(0); G_BAR; X_MMA0(0, 0); X_MMA1(0, 1); G_BAR; G_SCHED;
;             X_LDA(1, 1); G_STAGE_B(G_SB(1, 0), b3); G_STAGE_B(G_SB(1, 1), b3 + hstep); G_STAGE_AU(G_SA(1, 0), a3);
;             G_WAIT_V(8); G_WAIT_L(0); G_BAR; X_MMA0(1, 0); X_MMA1(1, 1); G_BAR; G_SCHED;
;         }
	v_add_u32_e32 v14, 0x18000, v194
	v_add_u32_e32 v30, 0x1c000, v194
	ds_read_b128 v[2:5], v14
	ds_read_b128 v[6:9], v14 offset:1024
	ds_read_b128 v[10:13], v14 offset:2048
	ds_read_b128 v[14:17], v14 offset:3072
	ds_read_b128 v[18:21], v30
	ds_read_b128 v[22:25], v30 offset:1024
	ds_read_b128 v[26:29], v30 offset:2048
	ds_read_b128 v[30:33], v30 offset:3072
	s_add_u32 s52, s52, s16
	s_addc_u32 s53, s53, 0
	v_lshl_add_u64 v[240:241], s[52:53], 0, v[166:167]
	s_add_u32 s52, s52, s3
	s_mov_b32 m0, s72
	s_addc_u32 s53, s53, 0
	ds_read_b128 v[196:199], v195 offset:32768
	ds_read_b128 v[200:203], v195 offset:33792
	ds_read_b128 v[204:207], v195 offset:34816
	ds_read_b128 v[208:211], v195 offset:35840
	ds_read_b128 v[212:215], v195 offset:36864
	ds_read_b128 v[216:219], v195 offset:37888
	ds_read_b128 v[232:235], v195 offset:38912
	ds_read_b128 v[236:239], v195 offset:39936
	global_load_lds_dwordx4 v[240:241], off
	v_lshl_add_u64 v[240:241], s[52:53], 0, v[166:167]
	s_mov_b32 m0, s86
	s_nop 0
	global_load_lds_dwordx4 v[240:241], off
	s_waitcnt vmcnt(8)
	s_waitcnt lgkmcnt(0)
	s_barrier
	s_setprio 1
	s_waitcnt lgkmcnt(0)
	v_mfma_scale_f32_16x16x128_f8f6f4 v[160:163], v[2:9], v[196:203], v[160:163], v222, v222 op_sel_hi:[0,0,0]
	v_mfma_scale_f32_16x16x128_f8f6f4 v[156:159], v[10:17], v[196:203], v[156:159], v222, v222 op_sel_hi:[0,0,0]
	v_mfma_scale_f32_16x16x128_f8f6f4 v[144:147], v[2:9], v[204:211], v[144:147], v222, v222 op_sel_hi:[0,0,0]
	v_mfma_scale_f32_16x16x128_f8f6f4 v[140:143], v[10:17], v[204:211], v[140:143], v222, v222 op_sel_hi:[0,0,0]
	v_mfma_scale_f32_16x16x128_f8f6f4 v[128:131], v[2:9], v[212:219], v[128:131], v222, v222 op_sel_hi:[0,0,0]
	v_mfma_scale_f32_16x16x128_f8f6f4 v[124:127], v[10:17], v[212:219], v[124:127], v222, v222 op_sel_hi:[0,0,0]
	v_mfma_scale_f32_16x16x128_f8f6f4 v[112:115], v[2:9], v[232:239], v[112:115], v222, v222 op_sel_hi:[0,0,0]
	v_mfma_scale_f32_16x16x128_f8f6f4 v[108:111], v[10:17], v[232:239], v[108:111], v222, v222 op_sel_hi:[0,0,0]
	s_setprio 0
	s_setprio 1
	v_mfma_scale_f32_16x16x128_f8f6f4 v[152:155], v[18:25], v[196:203], v[152:155], v222, v222 op_sel_hi:[0,0,0]
	v_mfma_scale_f32_16x16x128_f8f6f4 v[148:151], v[26:33], v[196:203], v[148:151], v222, v222 op_sel_hi:[0,0,0]
	v_mfma_scale_f32_16x16x128_f8f6f4 v[136:139], v[18:25], v[204:211], v[136:139], v222, v222 op_sel_hi:[0,0,0]
	v_mfma_scale_f32_16x16x128_f8f6f4 v[132:135], v[26:33], v[204:211], v[132:135], v222, v222 op_sel_hi:[0,0,0]
	v_mfma_scale_f32_16x16x128_f8f6f4 v[120:123], v[18:25], v[212:219], v[120:123], v222, v222 op_sel_hi:[0,0,0]
	v_mfma_scale_f32_16x16x128_f8f6f4 v[116:119], v[26:33], v[212:219], v[116:119], v222, v222 op_sel_hi:[0,0,0]
	v_mfma_scale_f32_16x16x128_f8f6f4 v[104:107], v[18:25], v[232:239], v[104:107], v222, v222 op_sel_hi:[0,0,0]
	v_mfma_scale_f32_16x16x128_f8f6f4 v[100:103], v[26:33], v[232:239], v[100:103], v222, v222 op_sel_hi:[0,0,0]
	s_setprio 0
	s_barrier
	s_mov_b32 m0, s77
	v_lshl_add_u64 v[174:175], v[174:175], 0, s[82:83]
	ds_read_b128 v[196:199], v195 offset:49152
	ds_read_b128 v[200:203], v195 offset:50176
	ds_read_b128 v[204:207], v195 offset:51200
	ds_read_b128 v[208:211], v195 offset:52224
	ds_read_b128 v[212:215], v195 offset:53248
	ds_read_b128 v[216:219], v195 offset:54272
	ds_read_b128 v[232:235], v195 offset:55296
	ds_read_b128 v[236:239], v195 offset:56320
	global_load_lds_dwordx4 v[174:175], off
	v_lshl_add_u64 v[174:175], v[176:177], 0, s[82:83]
	s_mov_b32 m0, s90
	s_nop 0
	global_load_lds_dwordx4 v[174:175], off
	v_lshl_add_u64 v[174:175], v[178:179], 0, s[82:83]
	s_mov_b32 m0, s95
	s_nop 0
	global_load_lds_dwordx4 v[174:175], off
	v_lshl_add_u64 v[174:175], v[180:181], 0, s[82:83]
	s_mov_b32 m0, s0
	s_nop 0
	global_load_lds_dwordx4 v[174:175], off
	v_lshl_add_u64 v[174:175], v[182:183], 0, s[82:83]
	s_mov_b32 m0, s91
	s_nop 0
	global_load_lds_dwordx4 v[174:175], off
	v_lshl_add_u64 v[174:175], v[184:185], 0, s[82:83]
	s_mov_b32 m0, s94
	s_nop 0
	global_load_lds_dwordx4 v[174:175], off
	s_waitcnt vmcnt(8)
	s_waitcnt lgkmcnt(0)
	s_barrier
	s_setprio 1
	s_waitcnt lgkmcnt(0)
	v_mfma_scale_f32_16x16x128_f8f6f4 v[96:99], v[2:9], v[196:203], v[96:99], v222, v222 op_sel_hi:[0,0,0]
	v_mfma_scale_f32_16x16x128_f8f6f4 v[92:95], v[10:17], v[196:203], v[92:95], v222, v222 op_sel_hi:[0,0,0]
	v_mfma_scale_f32_16x16x128_f8f6f4 v[80:83], v[2:9], v[204:211], v[80:83], v222, v222 op_sel_hi:[0,0,0]
	v_mfma_scale_f32_16x16x128_f8f6f4 v[76:79], v[10:17], v[204:211], v[76:79], v222, v222 op_sel_hi:[0,0,0]
	v_mfma_scale_f32_16x16x128_f8f6f4 v[62:65], v[2:9], v[212:219], v[62:65], v222, v222 op_sel_hi:[0,0,0]
	v_mfma_scale_f32_16x16x128_f8f6f4 v[58:61], v[10:17], v[212:219], v[58:61], v222, v222 op_sel_hi:[0,0,0]
	v_mfma_scale_f32_16x16x128_f8f6f4 v[46:49], v[2:9], v[232:239], v[46:49], v222, v222 op_sel_hi:[0,0,0]
	v_mfma_scale_f32_16x16x128_f8f6f4 v[42:45], v[10:17], v[232:239], v[42:45], v222, v222 op_sel_hi:[0,0,0]
	s_setprio 0
	s_setprio 1
	v_mfma_scale_f32_16x16x128_f8f6f4 v[88:91], v[18:25], v[196:203], v[88:91], v222, v222 op_sel_hi:[0,0,0]
	v_mfma_scale_f32_16x16x128_f8f6f4 v[84:87], v[26:33], v[196:203], v[84:87], v222, v222 op_sel_hi:[0,0,0]
	v_mfma_scale_f32_16x16x128_f8f6f4 v[72:75], v[18:25], v[204:211], v[72:75], v222, v222 op_sel_hi:[0,0,0]
	v_mfma_scale_f32_16x16x128_f8f6f4 v[68:71], v[26:33], v[204:211], v[68:71], v222, v222 op_sel_hi:[0,0,0]
	v_mfma_scale_f32_16x16x128_f8f6f4 v[54:57], v[18:25], v[212:219], v[54:57], v222, v222 op_sel_hi:[0,0,0]
	v_mfma_scale_f32_16x16x128_f8f6f4 v[50:53], v[26:33], v[212:219], v[50:53], v222, v222 op_sel_hi:[0,0,0]
	v_mfma_scale_f32_16x16x128_f8f6f4 v[38:41], v[18:25], v[232:239], v[38:41], v222, v222 op_sel_hi:[0,0,0]
	v_mfma_scale_f32_16x16x128_f8f6f4 v[34:37], v[26:33], v[232:239], v[34:37], v222, v222 op_sel_hi:[0,0,0]
	s_setprio 0
	s_barrier
	s_add_u32 s50, s50, 0x100
	s_addc_u32 s51, s51, 0
	s_add_u32 s11, s11, 0x100
	s_addc_u32 s13, s13, 0
	s_cmp_ge_u32 s24, s1
	s_mov_b32 s25, s24
	s_cbranch_scc1 .Lmy_peel_dn_exit

; #define G_BAR __builtin_amdgcn_s_barrier()
;     ...
;         }
;         if (wr == 0) G_BAR;
;         E(acc, cur, wr, wc, fr, fq);
.Lmy_peel_dn_exit:
	s_and_b64 vcc, exec, s[42:43]
	s_cbranch_vccz .LBB0_1099
	s_barrier

; template <int MODE, bool ROUTE, int H8> ...
;     ...
;         const int row0 = blk * 32, b = row0 / SEQ;
;         f32x4 gt[4], nsh[4], nsc[4];
; #pragma unroll
;         for (int jj = 0; jj < 4; ++jj) { gt[jj] = *(const f32x4*)(gate_mod + (size_t)b * 3072 + 2048 + 4 * F.lane + 256 * jj);
;             if (next_mod) { nsh[jj] = *(const f32x4*)(next_mod + (size_t)b * 3072 + 4 * F.lane + 256 * jj); nsc[jj] = *(const f32x4*)(next_mod + (size_t)b * 3072 + 1024 + 4 * F.lane + 256 * jj); }
;             else { nsh[jj] = (f32x4){0.f, 0.f, 0.f, 0.f}; nsc[jj] = nsh[jj]; } }
;         f32x4 xq[4]; u32x2 xhq[4], yq0[4], yq1[4];
;     ...
;         unsigned wq0 = 0u, wq1 = 0u;
;         LN_LOAD(0);
.LBB0_1229:
	s_ashr_i32 s24, s2, 31
	s_lshr_b32 s24, s24, 25
	s_add_i32 s24, s2, s24
	s_ashr_i32 s24, s24, 7
	s_mul_i32 s43, s24, 0x3000
	s_mul_hi_i32 s42, s24, 0x3000
	s_add_u32 s24, s6, s43
	s_addc_u32 s25, s7, s42
	v_lshlrev_b32_e32 v66, 2, v100
	v_lshl_add_u64 v[56:57], s[24:25], 0, v[66:67]
	v_add_co_u32_e32 v50, vcc, 0x2000, v56
	s_add_u32 s24, s44, s43
	s_nop 0
	v_addc_co_u32_e32 v51, vcc, 0, v57, vcc
	global_load_dwordx4 v[50:53], v[50:51], off
	s_addc_u32 s25, s29, s42
	v_lshl_add_u64 v[84:85], s[24:25], 0, v[66:67]
	s_mov_b64 s[4:5], 0x1000
	v_cndmask_b32_e64 v55, 0, 1, s[0:1]
	v_lshl_add_u64 v[86:87], v[84:85], 0, s[4:5]
	v_mov_b32_e32 v110, 1.0
	v_mov_b32_e32 v54, 0
	v_cmp_ne_u32_e64 s[42:43], 1, v55
	s_andn2_b64 vcc, exec, s[0:1]
	v_mov_b32_e32 v58, 0
	v_mov_b32_e32 v59, 0
	v_mov_b32_e32 v60, 0
	v_mov_b32_e32 v61, 0
	v_mov_b32_e32 v112, 1.0
	v_mov_b32_e32 v113, 1.0
	v_mov_b32_e32 v114, 1.0
	v_mov_b32_e32 v115, 1.0
	s_cbranch_vccnz .LBB0_1231
	global_load_dwordx4 v[202:205], v[86:87], off
	global_load_dwordx4 v[58:61], v[84:85], off
.LBB0_1231:
	s_mov_b64 s[4:5], 0x2000
	v_lshl_add_u64 v[74:75], v[56:57], 0, s[4:5]
	global_load_dwordx4 v[62:65], v[74:75], off offset:1024
	s_and_b64 vcc, exec, s[42:43]
	v_mov_b32_e32 v55, 0
	v_mov_b32_e32 v56, 0
	v_mov_b32_e32 v57, 0
	v_mov_b32_e32 v111, 1.0
	v_mov_b32_e32 v116, 1.0
	v_mov_b32_e32 v117, 1.0
	s_cbranch_vccnz .LBB0_1233
	global_load_dwordx4 v[206:209], v[86:87], off offset:1024
	global_load_dwordx4 v[54:57], v[84:85], off offset:1024
.LBB0_1233:
	global_load_dwordx4 v[68:71], v[74:75], off offset:2048
	v_mov_b32_e32 v118, 1.0
	v_mov_b32_e32 v72, 0
	s_and_b64 vcc, exec, s[42:43]
	v_mov_b32_e32 v76, 0
	v_mov_b32_e32 v77, 0
	v_mov_b32_e32 v78, 0
	v_mov_b32_e32 v79, 0
	v_mov_b32_e32 v120, 1.0
	v_mov_b32_e32 v121, 1.0
	v_mov_b32_e32 v122, 1.0
	v_mov_b32_e32 v123, 1.0
	s_cbranch_vccnz .LBB0_1235
	global_load_dwordx4 v[210:213], v[86:87], off offset:2048
	global_load_dwordx4 v[76:79], v[84:85], off offset:2048
.LBB0_1235:
	global_load_dwordx4 v[80:83], v[74:75], off offset:3072
	s_and_b64 vcc, exec, s[42:43]
	v_mov_b32_e32 v73, 0
	v_mov_b32_e32 v74, 0
	v_mov_b32_e32 v75, 0
	v_mov_b32_e32 v119, 1.0
	v_mov_b32_e32 v124, 1.0
	v_mov_b32_e32 v125, 1.0
	s_cbranch_vccnz .Lmy_ln2mod_202
	global_load_dwordx4 v[214:217], v[86:87], off offset:3072
	s_nop 0
	global_load_dwordx4 v[72:75], v[84:85], off offset:3072
	s_and_b64 vcc, exec, s[42:43]
	s_cbranch_vccnz .Lmy_ln2mod_202
	s_waitcnt vmcnt(0)
	v_pk_add_f32 v[114:115], v[204:205], 1.0 op_sel_hi:[1,0]
	v_pk_add_f32 v[112:113], v[202:203], 1.0 op_sel_hi:[1,0]
	v_pk_add_f32 v[116:117], v[208:209], 1.0 op_sel_hi:[1,0]
	v_pk_add_f32 v[110:111], v[206:207], 1.0 op_sel_hi:[1,0]
	v_pk_add_f32 v[122:123], v[212:213], 1.0 op_sel_hi:[1,0]
	v_pk_add_f32 v[120:121], v[210:211], 1.0 op_sel_hi:[1,0]
	v_pk_add_f32 v[124:125], v[216:217], 1.0 op_sel_hi:[1,0]
	v_pk_add_f32 v[118:119], v[214:215], 1.0 op_sel_hi:[1,0]
.Lmy_ln2mod_202:
.LBB0_1237:
	s_lshl_b32 s24, s2, 5
	s_ashr_i32 s25, s24, 31
	s_lshl_b64 s[42:43], s[24:25], 11
	v_lshl_add_u64 v[84:85], v[102:103], 0, s[42:43]
	s_lshl_b64 s[42:43], s[24:25], 12
	s_lshl_b64 s[24:25], s[24:25], 4
	s_add_u32 s24, s16, s24
	s_addc_u32 s25, s45, s25
	v_lshl_add_u64 v[126:127], v[108:109], 0, s[42:43]
	global_load_dwordx2 v[152:153], v[84:85], off nt
	global_load_dwordx2 v[88:89], v[84:85], off offset:512 nt
	global_load_dwordx2 v[92:93], v[84:85], off offset:1024 nt
	s_nop 0
	global_load_dwordx2 v[84:85], v[84:85], off offset:1536 nt
	s_nop 0
	global_load_dwordx2 v[154:155], v[126:127], off
	global_load_dwordx2 v[90:91], v[126:127], off offset:512
	global_load_dwordx2 v[94:95], v[126:127], off offset:1024
	global_load_dwordx2 v[86:87], v[126:127], off offset:1536
	global_load_dwordx2 v[158:159], v[126:127], off offset:2560
	global_load_dwordx2 v[156:157], v[126:127], off offset:3072
	global_load_dwordx2 v[96:97], v[126:127], off offset:3584
	global_load_dwordx2 v[98:99], v67, s[24:25] offset:4
	global_load_dwordx2 v[160:161], v[126:127], off offset:2048
	s_add_i32 s24, s54, 1
	s_ashr_i32 s25, s24, 31
	s_lshl_b64 s[42:43], s[24:25], 11
	v_lshl_add_u64 v[132:133], v[102:103], 0, s[42:43]
	s_lshl_b64 s[42:43], s[24:25], 12
	v_lshl_add_u64 v[142:143], v[108:109], 0, s[42:43]
	global_load_dwordx2 v[126:127], v[132:133], off nt
	global_load_dwordx2 v[128:129], v[132:133], off offset:512 nt
	global_load_dwordx2 v[130:131], v[132:133], off offset:1024 nt
	s_nop 0
	global_load_dwordx2 v[132:133], v[132:133], off offset:1536 nt
	s_nop 0
	global_load_dwordx2 v[140:141], v[142:143], off
	global_load_dwordx2 v[138:139], v[142:143], off offset:512
	global_load_dwordx2 v[136:137], v[142:143], off offset:1024
	global_load_dwordx2 v[134:135], v[142:143], off offset:1536
	global_load_dwordx2 v[148:149], v[142:143], off offset:2048
	global_load_dwordx2 v[146:147], v[142:143], off offset:2560
	global_load_dwordx2 v[144:145], v[142:143], off offset:3072
	s_nop 0
	global_load_dwordx2 v[142:143], v[142:143], off offset:3584
	s_lshl_b64 s[24:25], s[24:25], 4
	s_add_u32 s24, s16, s24
	s_addc_u32 s25, s45, s25
	global_load_dwordx2 v[150:151], v67, s[24:25] offset:4
	s_mov_b32 s56, 0
	s_waitcnt vmcnt(13)
	s_branch .LBB0_1240

; template <int MODE, bool ROUTE, int H8> ...
;     ...
;         const int row0 = blk * 32, b = row0 / SEQ;
;         f32x4 gt[4], nsh[4], nsc[4];
; #pragma unroll
;         for (int jj = 0; jj < 4; ++jj) { gt[jj] = *(const f32x4*)(gate_mod + (size_t)b * 3072 + 2048 + 4 * F.lane + 256 * jj);
;             if (next_mod) { nsh[jj] = *(const f32x4*)(next_mod + (size_t)b * 3072 + 4 * F.lane + 256 * jj); nsc[jj] = *(const f32x4*)(next_mod + (size_t)b * 3072 + 1024 + 4 * F.lane + 256 * jj); }
;             else { nsh[jj] = (f32x4){0.f, 0.f, 0.f, 0.f}; nsc[jj] = nsh[jj]; } }
;         f32x4 xq[4]; u32x2 xhq[4], yq0[4], yq1[4];
;     ...
;         unsigned wq0 = 0u, wq1 = 0u;
;         LN_LOAD(0);
.LBB0_1267:
	s_ashr_i32 s2, s16, 31
	s_lshr_b32 s2, s2, 25
	s_add_i32 s2, s16, s2
	s_ashr_i32 s2, s2, 7
	s_mul_i32 s11, s2, 0x3000
	s_mul_hi_i32 s10, s2, 0x3000
	s_add_u32 s2, s6, s11
	s_addc_u32 s3, s7, s10
	v_lshlrev_b32_e32 v66, 2, v100
	v_lshl_add_u64 v[56:57], s[2:3], 0, v[66:67]
	v_add_co_u32_e32 v50, vcc, 0x2000, v56
	s_add_u32 s2, s44, s11
	s_nop 0
	v_addc_co_u32_e32 v51, vcc, 0, v57, vcc
	global_load_dwordx4 v[50:53], v[50:51], off
	s_addc_u32 s3, s29, s10
	v_lshl_add_u64 v[84:85], s[2:3], 0, v[66:67]
	s_mov_b64 s[2:3], 0x1000
	v_cndmask_b32_e64 v55, 0, 1, s[0:1]
	v_lshl_add_u64 v[86:87], v[84:85], 0, s[2:3]
	v_mov_b32_e32 v110, 1.0
	v_mov_b32_e32 v54, 0
	v_cmp_ne_u32_e64 s[42:43], 1, v55
	s_andn2_b64 vcc, exec, s[0:1]
	v_mov_b32_e32 v58, 0
	v_mov_b32_e32 v59, 0
	v_mov_b32_e32 v60, 0
	v_mov_b32_e32 v61, 0
	v_mov_b32_e32 v112, 1.0
	v_mov_b32_e32 v113, 1.0
	v_mov_b32_e32 v114, 1.0
	v_mov_b32_e32 v115, 1.0
	s_cbranch_vccnz .LBB0_1269
	global_load_dwordx4 v[196:199], v[86:87], off
	global_load_dwordx4 v[58:61], v[84:85], off
.LBB0_1269:
	s_mov_b64 s[2:3], 0x2000
	v_lshl_add_u64 v[74:75], v[56:57], 0, s[2:3]
	global_load_dwordx4 v[62:65], v[74:75], off offset:1024
	s_and_b64 vcc, exec, s[42:43]
	v_mov_b32_e32 v55, 0
	v_mov_b32_e32 v56, 0
	v_mov_b32_e32 v57, 0
	v_mov_b32_e32 v111, 1.0
	v_mov_b32_e32 v116, 1.0
	v_mov_b32_e32 v117, 1.0
	s_cbranch_vccnz .LBB0_1271
	global_load_dwordx4 v[200:203], v[86:87], off offset:1024
	global_load_dwordx4 v[54:57], v[84:85], off offset:1024
.LBB0_1271:
	global_load_dwordx4 v[68:71], v[74:75], off offset:2048
	v_mov_b32_e32 v118, 1.0
	v_mov_b32_e32 v72, 0
	s_and_b64 vcc, exec, s[42:43]
	v_mov_b32_e32 v76, 0
	v_mov_b32_e32 v77, 0
	v_mov_b32_e32 v78, 0
	v_mov_b32_e32 v79, 0
	v_mov_b32_e32 v120, 1.0
	v_mov_b32_e32 v121, 1.0
	v_mov_b32_e32 v122, 1.0
	v_mov_b32_e32 v123, 1.0
	s_cbranch_vccnz .LBB0_1273
	global_load_dwordx4 v[204:207], v[86:87], off offset:2048
	global_load_dwordx4 v[76:79], v[84:85], off offset:2048
.LBB0_1273:
	global_load_dwordx4 v[80:83], v[74:75], off offset:3072
	s_and_b64 vcc, exec, s[42:43]
	v_mov_b32_e32 v73, 0
	v_mov_b32_e32 v74, 0
	v_mov_b32_e32 v75, 0
	v_mov_b32_e32 v119, 1.0
	v_mov_b32_e32 v124, 1.0
	v_mov_b32_e32 v125, 1.0
	s_cbranch_vccnz .Lmy_ln2mod_196
	global_load_dwordx4 v[208:211], v[86:87], off offset:3072
	s_nop 0
	global_load_dwordx4 v[72:75], v[84:85], off offset:3072
	s_and_b64 vcc, exec, s[42:43]
	s_cbranch_vccnz .Lmy_ln2mod_196
	s_waitcnt vmcnt(0)
	v_pk_add_f32 v[114:115], v[198:199], 1.0 op_sel_hi:[1,0]
	v_pk_add_f32 v[112:113], v[196:197], 1.0 op_sel_hi:[1,0]
	v_pk_add_f32 v[116:117], v[202:203], 1.0 op_sel_hi:[1,0]
	v_pk_add_f32 v[110:111], v[200:201], 1.0 op_sel_hi:[1,0]
	v_pk_add_f32 v[122:123], v[206:207], 1.0 op_sel_hi:[1,0]
	v_pk_add_f32 v[120:121], v[204:205], 1.0 op_sel_hi:[1,0]
	v_pk_add_f32 v[124:125], v[210:211], 1.0 op_sel_hi:[1,0]
	v_pk_add_f32 v[118:119], v[208:209], 1.0 op_sel_hi:[1,0]
.Lmy_ln2mod_196:
.LBB0_1275:
	s_lshl_b32 s2, s16, 5
	s_ashr_i32 s3, s2, 31
	s_lshl_b64 s[2:3], s[2:3], 11
	v_lshl_add_u64 v[86:87], v[102:103], 0, s[2:3]
	v_lshl_add_u64 v[98:99], v[104:105], 0, s[2:3]
	global_load_dwordx2 v[92:93], v[86:87], off offset:1024 nt
	global_load_dwordx2 v[84:85], v[86:87], off offset:1536 nt
	global_load_dwordx2 v[96:97], v[86:87], off nt
	global_load_dwordx2 v[88:89], v[86:87], off offset:512 nt
	s_nop 0
	global_load_dwordx2 v[86:87], v[98:99], off offset:1536
	global_load_dwordx2 v[94:95], v[98:99], off offset:1024
	global_load_dwordx2 v[90:91], v[98:99], off offset:512
	s_nop 0
	global_load_dwordx2 v[98:99], v[98:99], off
	s_add_i32 s2, s46, 1
	s_ashr_i32 s3, s2, 31
	s_lshl_b64 s[2:3], s[2:3], 11
	v_lshl_add_u64 v[132:133], v[102:103], 0, s[2:3]
	v_lshl_add_u64 v[134:135], v[104:105], 0, s[2:3]
	global_load_dwordx2 v[126:127], v[132:133], off nt
	global_load_dwordx2 v[128:129], v[132:133], off offset:512 nt
	global_load_dwordx2 v[130:131], v[132:133], off offset:1024 nt
	s_nop 0
	global_load_dwordx2 v[132:133], v[132:133], off offset:1536 nt
	s_nop 0
	global_load_dwordx2 v[140:141], v[134:135], off
	global_load_dwordx2 v[138:139], v[134:135], off offset:512
	global_load_dwordx2 v[136:137], v[134:135], off offset:1024
	s_nop 0
	global_load_dwordx2 v[134:135], v[134:135], off offset:1536
	s_mov_b32 s42, 0
	s_waitcnt vmcnt(8)
	s_branch .LBB0_1278
